# attention MLA+differential tile loops: next-tile LDS-DMA block issued in the shadow of the first P.V MFMAs instead of at the interval head; next interval's first V fragments read before the closing ba
# baseline (speedup 1.0000x reference)
; template <int TYPE>
; __device__ __forceinline__ void attn_mfma_unit2(const AttnCtx& A, unsigned char* ws, LAS unsigned char* lds, int tid, const AUnit& u) {
;     ...
;     const int qrow = u.qrow0 + 32 * w + q;
;     bf16x8 qf[NKK];
; #pragma unroll
;     for (int kk = 0; kk < NKK; ++kk) qf[kk] = *(const bf16x8*)(Qg + (size_t)qrow * ld + 16 * kk + 8 * h2);
;     int lo = 0, nlat = u.isctx ? 0 : 64, qr = 0, qc = 0, r0w = 0, c0 = 0;
;     if (TYPE == 0 && !u.isctx) {
;         int a = 4 * u.g - 4; lo = a < 0 ? 0 : (a > 56 ? 56 : a); int hb = 4 * u.g + 3 - 4; hb = hb < 0 ? 0 : (hb > 56 ? 56 : hb); nlat = hb + 8 - lo;
;         qr = 4 * u.g + (w >> 1); qc = 32 * (w & 1) + q; int t = qr - 4; r0w = t < 0 ? 0 : (t > 56 ? 56 : t); t = qc - 8; c0 = t < 0 ? 0 : (t > 48 ? 48 : t);
;         LAS float* rp = (LAS float*)(lds + A2_RPB);
;         if (tid < 465) rp[tid] = A.rpb[u.h * 465 + tid] * LOG2E;
;     }
;     const int nt = 4 + nlat;
;     unsigned goff[NIW];
; #pragma unroll
;     for (int m = 0; m < NIW; ++m) {
;         if (m < NIK) { const int p = 64 * (w + 8 * m) + lane, row = p / NKC, slot = p % NKC; const int c = DQK == 128 ? (slot ^ (row & 15)) : (slot ^ ((row >> 1) & 7)); goff[m] = (unsigned)(swap23(row) * ld + 8 * c); }
;         else { const int p = 64 * (w + 8 * (m - NIK)) + lane, ch = p >> 3, slot = p & 7; const int c = slot ^ ((ch >> 1) & 7); goff[m] = (unsigned)(ch * M + 8 * c); }
;     }
;     const unsigned ldsw = (unsigned)w * 1024u;
;     unsigned kbase[NKB], vbase[4];
; #pragma unroll
;     for (int i = 0; i < NKB; ++i) kbase[i] = (unsigned)(q * PITCH + 16 * (DQK == 128 ? ((2 * i + h2) ^ (q & 15)) : ((2 * i + h2) ^ ((q >> 1) & 7))));
; #pragma unroll
;     for (int i = 0; i < 4; ++i) vbase[i] = (unsigned)(KB + q * 128 + 16 * ((2 * i + h2) ^ ((q >> 1) & 7)));
;     ...
;     A2_DMA(0, 0);
;     asm volatile("s_waitcnt lgkmcnt(0)" ::: "memory");
;     A2_WAITN(0); A2_BAR();
;     ...
;     unsigned kc[NKB], vc[4];
;     int scur = 0, snxt = STG, sprv = 0;
;     if (w < 4 && !ATTN_ALLLATE) {
;         for (int ti = 0; ti < nt; ++ti) {
;             if (ti + 1 < nt) A2_DMA(ti + 1, snxt);
;             if (A2_ACTIVE(ti)) { A2_SETKC(scur); A2_SETVC(scur); A2_QK(sA0, sA1, ti, 0); A2_PSM(sA0, sA1); A2_FSM_PV(sA0, sA1, 0); }
;             A2_WAITN(0); A2_BAR();
;             sprv = scur; scur = snxt; snxt = snxt == 2 * STG ? 0 : snxt + STG;
;         }
;     } else {
.LBB0_2780:
	s_lshl_b32 s28, s16, 7
	s_ashr_i32 s29, s28, 31
	s_xor_b64 s[36:37], s[0:1], -1
	s_lshl_b64 s[6:7], s[28:29], 1
	v_readlane_b32 s9, v253, 10
	s_add_u32 s9, s9, s6
	v_readlane_b32 s11, v253, 11
	s_addc_u32 s11, s11, s7
	s_lshl_b32 s12, s42, 7
	s_add_u32 s14, s9, s12
	s_addc_u32 s15, s11, 0
	v_readlane_b32 s9, v253, 12
	s_add_u32 s6, s9, s6
	v_readlane_b32 s9, v253, 13
	s_addc_u32 s7, s9, s7
	s_add_u32 s6, s6, s12
	s_addc_u32 s7, s7, 0
	s_add_i32 s9, s28, 0x300
	s_mul_hi_i32 s11, s9, 0x4400
	s_mulk_i32 s9, 0x4400
	s_add_u32 s12, s60, s9
	s_addc_u32 s13, s61, s11
	s_lshl_b32 s9, s10, 5
	v_and_b32_e32 v12, 31, v2
	s_add_i32 s43, s9, s19
	v_bfe_u32 v13, v2, 5, 1
	v_add_u32_e32 v0, s43, v12
	v_mov_b64_e32 v[4:5], s[14:15]
	s_movk_i32 s11, 0x500
	v_mad_i64_i32 v[4:5], s[14:15], v0, s11, v[4:5]
	v_lshlrev_b32_e32 v0, 4, v13
	v_lshl_add_u64 v[4:5], v[4:5], 0, v[0:1]
	v_mov_b32_e32 v0, s8
	s_movk_i32 s14, 0xffc0
	global_load_dwordx4 v[124:127], v[4:5], off
	global_load_dwordx4 v[120:123], v[4:5], off offset:32
	global_load_dwordx4 v[116:119], v[4:5], off offset:64
	global_load_dwordx4 v[112:115], v[4:5], off offset:96
	v_bfi_b32 v4, s14, v0, v2
	s_ashr_i32 s14, s8, 31
	s_lshr_b32 s14, s14, 29
	v_add_u32_e32 v0, s14, v4
	v_ashrrev_i32_e32 v5, 3, v0
	v_and_b32_e32 v0, 0x1ffffff8, v0
	v_sub_u32_e32 v0, v4, v0
	v_lshrrev_b32_e32 v6, 1, v5
	v_and_b32_e32 v7, 0x1fffff3, v5
	v_lshlrev_b32_e32 v5, 1, v5
	v_bitop3_b32 v0, v6, v0, 7 bitop3:0x6c
	v_and_b32_e32 v5, 8, v5
	v_and_b32_e32 v6, 4, v6
	v_or3_b32 v5, v7, v5, v6
	s_movk_i32 s14, 0x280
	v_mul_lo_u32 v5, v5, s14
	s_and_b32 s11, s8, 0xffffffc0
	v_lshl_add_u32 v0, v0, 3, v5
	v_lshrrev_b32_e32 v5, 3, v4
	v_lshrrev_b32_e32 v4, 4, v4
	v_and_b32_e32 v3, 63, v2
	v_xor_b32_e32 v4, v4, v2
	s_addk_i32 s11, 0x200
	s_lshl_b32 s45, s18, 8
	v_mul_lo_u32 v5, v5, s82
	v_lshlrev_b32_e32 v4, 3, v4
	v_or_b32_e32 v3, s11, v3
	s_add_i32 s38, s45, 0x2000
	v_and_or_b32 v128, v4, 56, v5
	v_lshrrev_b32_e32 v4, 4, v3
	s_lshl_b32 s11, s10, 10
	s_ashr_i32 s39, s38, 31
	s_mul_i32 s14, s38, 0x500
	v_xor_b32_e32 v4, v4, v2
	v_lshrrev_b32_e32 v3, 3, v3
	s_mul_hi_i32 s15, s38, 0x500
	s_add_u32 s14, s6, s14
	v_lshlrev_b32_e32 v4, 3, v4
	v_mul_lo_u32 v3, v3, s82
	s_addc_u32 s15, s7, s15
	s_lshl_b64 s[46:47], s[38:39], 1
	v_and_or_b32 v130, v4, 56, v3
	s_add_u32 s46, s12, s46
	v_lshlrev_b64 v[4:5], 1, v[0:1]
	s_addc_u32 s47, s13, s47
	v_lshl_add_u64 v[6:7], s[14:15], 0, v[4:5]
	s_add_i32 s14, s11, 0
	s_mov_b32 m0, s14
	v_mov_b32_e32 v129, v1
	global_load_lds_dwordx4 v[6:7], off
	v_lshlrev_b64 v[6:7], 1, v[128:129]
	s_add_i32 m0, s14, 0x2000
	v_lshl_add_u64 v[8:9], s[46:47], 0, v[6:7]
	v_mov_b32_e32 v131, v1
	global_load_lds_dwordx4 v[8:9], off
	v_lshlrev_b64 v[8:9], 1, v[130:131]
	v_lshl_add_u64 v[132:133], s[6:7], 0, v[4:5]
	s_add_i32 s6, s45, 0x2040
	v_lshl_add_u64 v[10:11], s[46:47], 0, v[8:9]
	s_add_i32 m0, s14, 0x4000
	s_ashr_i32 s7, s6, 31
	global_load_lds_dwordx4 v[10:11], off
	s_lshl_b64 s[46:47], s[6:7], 1
	s_waitcnt lgkmcnt(0)
	s_add_u32 s46, s12, s46
	s_waitcnt vmcnt(0)
	s_barrier
	s_addc_u32 s47, s13, s47
	v_mad_i64_i32 v[4:5], s[6:7], s6, v242, v[132:133]
	s_add_i32 m0, s14, 0x6000
	v_lshrrev_b32_e32 v3, 1, v2
	global_load_lds_dwordx4 v[4:5], off
	s_add_i32 m0, s14, 0x8000
	v_lshl_add_u64 v[4:5], s[46:47], 0, v[6:7]
	global_load_lds_dwordx4 v[4:5], off
	v_lshl_add_u64 v[4:5], s[46:47], 0, v[8:9]
	s_add_i32 m0, s14, 0xa000
	v_bfe_u32 v2, v2, 1, 3
	global_load_lds_dwordx4 v[4:5], off
	v_bitop3_b32 v3, v13, v3, 7 bitop3:0x78
	v_bitop3_b32 v4, v13, v2, 2 bitop3:0x36
	v_bitop3_b32 v5, v13, v2, 4 bitop3:0x36
	v_bitop3_b32 v2, v13, v2, 6 bitop3:0x36
	v_lshlrev_b32_e32 v0, 7, v12
	v_lshlrev_b32_e32 v3, 4, v3
	v_lshlrev_b32_e32 v4, 4, v4
	v_lshlrev_b32_e32 v5, 4, v5
	v_lshlrev_b32_e32 v2, 4, v2
	v_add3_u32 v134, 0, v2, v0
	v_add3_u32 v135, 0, v5, v0
	v_add3_u32 v136, 0, v4, v0
	v_add3_u32 v137, 0, v3, v0
	ds_read_b128 v[34:37], v134 offset:4096
	ds_read_b128 v[38:41], v134
	ds_read_b128 v[42:45], v135 offset:4096
	ds_read_b128 v[46:49], v135
	ds_read_b128 v[50:53], v136 offset:4096
	ds_read_b128 v[54:57], v136
	ds_read_b128 v[58:61], v137 offset:4096
	ds_read_b128 v[62:65], v137
	s_mov_b32 s15, 1
	s_movk_i32 s47, 0x6000
	v_readlane_b32 s64, v254, 25
	v_readlane_b32 s65, v254, 26
	v_readlane_b32 s66, v254, 27
	v_readlane_b32 s67, v254, 28
	v_readlane_b32 s68, v254, 29
	v_readlane_b32 s69, v254, 30
	v_readlane_b32 s70, v254, 31
	v_readlane_b32 s71, v254, 32
	v_readlane_b32 s72, v254, 33
	v_readlane_b32 s73, v254, 34
	v_readlane_b32 s74, v254, 35
	v_readlane_b32 s75, v254, 36
	v_readlane_b32 s76, v254, 37
	v_readlane_b32 s77, v254, 38
	v_readlane_b32 s78, v254, 39
	v_readlane_b32 s79, v254, 40
	s_mov_b32 s65, s64
	s_mov_b32 s66, s64
	s_mov_b32 s67, s64
	s_mov_b32 s68, s64
	s_mov_b32 s69, s64
	s_mov_b32 s70, s64
	s_mov_b32 s71, s64
	s_mov_b32 s72, s64
	s_mov_b32 s73, s64
	s_mov_b32 s74, s64
	s_mov_b32 s75, s64
	s_mov_b32 s76, s64
	s_mov_b32 s77, s64
	s_mov_b32 s78, s64
	s_mov_b32 s79, s64
	v_mov_b64_e32 v[2:3], s[64:65]
	s_mov_b32 s48, s64
	v_mov_b64_e32 v[4:5], s[66:67]
	v_mov_b64_e32 v[6:7], s[68:69]
	v_mov_b64_e32 v[8:9], s[70:71]
	v_mov_b64_e32 v[10:11], s[72:73]
	v_mov_b64_e32 v[12:13], s[74:75]
	v_mov_b64_e32 v[14:15], s[76:77]
	v_mov_b64_e32 v[16:17], s[78:79]
	v_writelane_b32 v254, s48, 25
	s_waitcnt vmcnt(0) lgkmcnt(0)
	v_mfma_f32_32x32x16_bf16 v[18:33], v[62:65], v[124:127], v[2:17]
	v_writelane_b32 v254, s49, 26
	v_writelane_b32 v254, s50, 27
	v_writelane_b32 v254, s51, 28
	v_writelane_b32 v254, s52, 29
	v_writelane_b32 v254, s53, 30
	v_writelane_b32 v254, s54, 31
	v_writelane_b32 v254, s55, 32
	v_writelane_b32 v254, s56, 33
	v_mfma_f32_32x32x16_bf16 v[18:33], v[54:57], v[120:123], v[18:33]
	v_writelane_b32 v254, s57, 34
	v_writelane_b32 v254, s58, 35
	v_writelane_b32 v254, s59, 36
	v_writelane_b32 v254, s60, 37
	v_writelane_b32 v254, s61, 38
	v_writelane_b32 v254, s62, 39
	v_writelane_b32 v254, s63, 40
	v_mfma_f32_32x32x16_bf16 v[18:33], v[46:49], v[116:119], v[18:33]
	v_mfma_f32_32x32x16_bf16 v[18:33], v[38:41], v[112:115], v[18:33]
	v_mfma_f32_32x32x16_bf16 v[2:17], v[58:61], v[124:127], v[2:17]
	s_nop 10
	v_max_f32_e32 v0, v19, v19
	v_max_f32_e32 v38, v18, v18
	v_max_f32_e32 v0, v38, v0
	v_max3_f32 v0, v0, v20, v21
	v_max3_f32 v0, v0, v22, v23
	v_max3_f32 v0, v0, v24, v25
	v_max3_f32 v0, v0, v26, v27
	v_mfma_f32_32x32x16_bf16 v[2:17], v[50:53], v[120:123], v[2:17]
	v_max3_f32 v0, v0, v28, v29
	v_max3_f32 v0, v0, v30, v31
	v_max3_f32 v0, v0, v32, v33
	s_lshl_b32 s11, s18, 12
	s_waitcnt vmcnt(0)
	s_barrier
; #define A2_SETVC(SOFF) _Pragma("unroll") for (int _i = 0; _i < 4; ++_i) vc[_i] = vbase[_i] + (unsigned)(SOFF)
; template <int TYPE>
; __device__ __forceinline__ void attn_mfma_unit2(const AttnCtx& A, unsigned char* ws, LAS unsigned char* lds, int tid, const AUnit& u) {
;     ...
;         for (int ti = 0; ti < nt; ++ti) {
;             if (ti + 1 < nt) A2_DMA(ti + 1, snxt);
;             if (actP) { A2_SETVC(sprv); A2_FSM_PV(sA0, sA1, 0); }
	v_mfma_f32_32x32x16_bf16 v[2:17], v[42:45], v[116:119], v[2:17]
	s_add_i32 s39, s11, 0xffffff40
	s_and_b64 s[48:49], s[0:1], exec
	s_mov_b32 s7, 0
	s_cselect_b32 s45, 0x42, 2
	s_mov_b32 s6, 0xc000
	v_mov_b32_e32 v139, 0
	v_mfma_f32_32x32x16_bf16 v[2:17], v[34:37], v[112:115], v[2:17]
	s_nop 11
	v_max3_f32 v0, v0, v2, v3
	v_max3_f32 v0, v0, v4, v5
	v_max3_f32 v0, v0, v6, v7
	v_max3_f32 v0, v0, v8, v9
	v_max3_f32 v0, v0, v10, v11
	v_max3_f32 v0, v0, v12, v13
	v_max3_f32 v0, v0, v14, v15
	v_max3_f32 v0, v0, v16, v17
	v_mov_b32_e32 v34, v0
	s_nop 1
	v_permlane32_swap_b32_e32 v0, v34
	v_max_f32_e32 v34, v34, v34
	v_max_f32_e32 v0, v0, v0
	v_max_f32_e32 v0, v0, v34
	v_sub_f32_e32 v93, v15, v0
	v_sub_f32_e32 v92, v14, v0
	v_mov_b32_e32 v14, v1
	v_mov_b32_e32 v15, v1
	v_add_f32_e32 v138, 0, v0
	v_sub_f32_e32 v111, v33, v0
	v_sub_f32_e32 v110, v32, v0
	v_sub_f32_e32 v109, v31, v0
	v_sub_f32_e32 v108, v30, v0
	v_sub_f32_e32 v107, v29, v0
	v_sub_f32_e32 v106, v28, v0
	v_sub_f32_e32 v105, v27, v0
	v_sub_f32_e32 v104, v26, v0
	v_sub_f32_e32 v103, v25, v0
	v_sub_f32_e32 v102, v24, v0
	v_sub_f32_e32 v101, v23, v0
	v_sub_f32_e32 v100, v22, v0
	v_sub_f32_e32 v99, v21, v0
	v_sub_f32_e32 v98, v20, v0
	v_sub_f32_e32 v97, v19, v0
	v_sub_f32_e32 v96, v18, v0
	v_sub_f32_e32 v95, v17, v0
	v_sub_f32_e32 v94, v16, v0
	v_sub_f32_e32 v91, v13, v0
	v_sub_f32_e32 v90, v12, v0
	v_sub_f32_e32 v89, v11, v0
	v_sub_f32_e32 v88, v10, v0
	v_sub_f32_e32 v87, v9, v0
	v_sub_f32_e32 v86, v8, v0
	v_sub_f32_e32 v85, v7, v0
	v_sub_f32_e32 v84, v6, v0
	v_sub_f32_e32 v83, v5, v0
	v_sub_f32_e32 v82, v4, v0
	v_sub_f32_e32 v81, v3, v0
	v_sub_f32_e32 v80, v2, v0
	v_mov_b32_e32 v0, v1
	v_mov_b32_e32 v2, v1
	v_mov_b32_e32 v3, v1
	v_mov_b32_e32 v4, v1
	v_mov_b32_e32 v5, v1
	v_mov_b32_e32 v6, v1
	v_mov_b32_e32 v7, v1
	v_mov_b32_e32 v8, v1
	v_mov_b32_e32 v9, v1
	v_mov_b32_e32 v10, v1
	v_mov_b32_e32 v11, v1
	v_mov_b32_e32 v12, v1
	v_mov_b32_e32 v13, v1
	v_mov_b64_e32 v[30:31], v[14:15]
	v_mov_b64_e32 v[46:47], v[14:15]
	v_mov_b64_e32 v[62:63], v[14:15]
	v_mov_b64_e32 v[78:79], v[14:15]
	v_mov_b64_e32 v[28:29], v[12:13]
	v_mov_b64_e32 v[26:27], v[10:11]
	v_mov_b64_e32 v[24:25], v[8:9]
	v_mov_b64_e32 v[22:23], v[6:7]
	v_mov_b64_e32 v[20:21], v[4:5]
	v_mov_b64_e32 v[18:19], v[2:3]
	v_mov_b64_e32 v[16:17], v[0:1]
	v_mov_b64_e32 v[44:45], v[12:13]
	v_mov_b64_e32 v[42:43], v[10:11]
	v_mov_b64_e32 v[40:41], v[8:9]
	v_mov_b64_e32 v[38:39], v[6:7]
	v_mov_b64_e32 v[36:37], v[4:5]
	v_mov_b64_e32 v[34:35], v[2:3]
	v_mov_b64_e32 v[32:33], v[0:1]
	v_mov_b64_e32 v[60:61], v[12:13]
	v_mov_b64_e32 v[58:59], v[10:11]
	v_mov_b64_e32 v[56:57], v[8:9]
	v_mov_b64_e32 v[54:55], v[6:7]
	v_mov_b64_e32 v[52:53], v[4:5]
	v_mov_b64_e32 v[50:51], v[2:3]
	v_mov_b64_e32 v[48:49], v[0:1]
	v_mov_b64_e32 v[76:77], v[12:13]
	v_mov_b64_e32 v[74:75], v[10:11]
	v_mov_b64_e32 v[72:73], v[8:9]
	v_mov_b64_e32 v[70:71], v[6:7]
	v_mov_b64_e32 v[68:69], v[4:5]
	v_mov_b64_e32 v[66:67], v[2:3]
	v_mov_b64_e32 v[64:65], v[0:1]
	v_add_u32_e32 v0, s7, v137
	ds_read_b128 v[2:5], v0 offset:8192
	ds_read_b128 v[6:9], v0 offset:12288
	ds_read_b128 v[10:13], v0 offset:16384
	ds_read_b128 v[140:143], v0 offset:20480
.LBB0_2781:
	s_mov_b32 s48, s7
	s_mov_b32 s7, s47
	v_exp_f32_e32 v14, v96
	v_exp_f32_e32 v144, v97
	v_exp_f32_e32 v98, v98
	v_exp_f32_e32 v146, v99
	v_exp_f32_e32 v15, v100
	v_exp_f32_e32 v145, v101
	v_exp_f32_e32 v99, v102
	v_exp_f32_e32 v147, v103
	v_add_u32_e32 v0, s48, v136
	v_pk_add_f32 v[96:97], v[14:15], v[144:145]
	v_pk_add_f32 v[100:101], v[98:99], v[146:147]
	s_nop 0
	v_pk_add_f32 v[96:97], v[96:97], v[100:101]
	v_cvt_pk_bf16_f32 v99, v99, v147
	v_pk_add_f32 v[156:157], v[96:97], v[96:97] op_sel_hi:[0,1]
	v_cvt_pk_bf16_f32 v96, v14, v144
	v_cvt_pk_bf16_f32 v97, v98, v146
	v_cvt_pk_bf16_f32 v98, v15, v145
	ds_read_b128 v[100:103], v0 offset:8192
	ds_read_b128 v[144:147], v0 offset:12288
	ds_read_b128 v[148:151], v0 offset:16384
	ds_read_b128 v[152:155], v0 offset:20480
	s_waitcnt lgkmcnt(0)
	v_mfma_f32_32x32x16_bf16 v[64:79], v[2:5], v[96:99], v[64:79]
	v_mfma_f32_32x32x16_bf16 v[48:63], v[6:9], v[96:99], v[48:63]
	v_mfma_f32_32x32x16_bf16 v[32:47], v[10:13], v[96:99], v[32:47]
	v_mfma_f32_32x32x16_bf16 v[16:31], v[140:143], v[96:99], v[16:31]
	s_add_i32 s46, s15, 1
	s_cmp_lt_u32 s15, 3
	s_cselect_b32 s100, s46, s15
	s_cselect_b32 s101, s38, s39
	s_lshl_b32 s100, s100, 6
	s_add_i32 s100, s100, s101
	s_ashr_i32 s101, s100, 31
	s_lshl_b64 s[50:51], s[100:101], 1
	s_add_u32 s50, s12, s50
	v_mad_i64_i32 v[2:3], s[100:101], s100, v242, v[132:133]
	s_addc_u32 s51, s13, s51
	s_add_i32 s100, s14, s6
	s_mov_b32 m0, s100
	s_nop 0
	global_load_lds_dwordx4 v[2:3], off
	s_add_i32 m0, s100, 0x2000
	v_lshl_add_u64 v[2:3], v[128:129], 1, s[50:51]
	global_load_lds_dwordx4 v[2:3], off
	v_lshl_add_u64 v[2:3], v[130:131], 1, s[50:51]
	s_add_i32 m0, s100, 0x4000
	s_nop 0
	global_load_lds_dwordx4 v[2:3], off
	v_exp_f32_e32 v2, v104
	v_exp_f32_e32 v4, v105
	v_exp_f32_e32 v3, v106
	v_exp_f32_e32 v5, v107
	v_exp_f32_e32 v6, v108
	v_exp_f32_e32 v8, v109
	v_exp_f32_e32 v7, v110
	v_exp_f32_e32 v9, v111
	v_pk_add_f32 v[10:11], v[2:3], v[4:5]
	v_add_u32_e32 v0, s48, v135
	v_pk_add_f32 v[14:15], v[10:11], v[10:11] op_sel_hi:[0,1]
	v_pk_add_f32 v[10:11], v[6:7], v[8:9]
	v_cvt_pk_bf16_f32 v2, v2, v4
	v_pk_add_f32 v[140:141], v[10:11], v[10:11] op_sel_hi:[0,1]
	v_cvt_pk_bf16_f32 v3, v3, v5
	v_cvt_pk_bf16_f32 v4, v6, v8
	v_cvt_pk_bf16_f32 v5, v7, v9
	ds_read_b128 v[6:9], v0 offset:8192
	ds_read_b128 v[10:13], v0 offset:12288
	ds_read_b128 v[96:99], v0 offset:16384
	ds_read_b128 v[104:107], v0 offset:20480
	v_mfma_f32_32x32x16_bf16 v[64:79], v[100:103], v[2:5], v[64:79]
	v_mfma_f32_32x32x16_bf16 v[48:63], v[144:147], v[2:5], v[48:63]
	v_mfma_f32_32x32x16_bf16 v[32:47], v[148:151], v[2:5], v[32:47]
	v_mfma_f32_32x32x16_bf16 v[16:31], v[152:155], v[2:5], v[16:31]
	v_exp_f32_e32 v0, v80
	v_exp_f32_e32 v2, v81
	v_exp_f32_e32 v3, v82
	v_exp_f32_e32 v4, v83
	v_exp_f32_e32 v5, v84
	v_exp_f32_e32 v14, v85
	v_exp_f32_e32 v80, v86
	v_exp_f32_e32 v81, v87
	v_add_f32_e32 v143, v0, v2
	v_cvt_pk_bf16_f32 v2, v0, v2
	v_add_u32_e32 v0, s48, v134
	v_add_f32_e32 v145, v3, v4
	v_add_f32_e32 v147, v5, v14
	v_add_f32_e32 v149, v80, v81
	v_cvt_pk_bf16_f32 v3, v3, v4
	v_cvt_pk_bf16_f32 v4, v5, v14
	v_cvt_pk_bf16_f32 v5, v80, v81
	ds_read_b128 v[80:83], v0 offset:8192
	ds_read_b128 v[84:87], v0 offset:12288
	ds_read_b128 v[100:103], v0 offset:16384
	ds_read_b128 v[108:111], v0 offset:20480
	s_waitcnt lgkmcnt(0)
; #define A2_WAITN(n) asm volatile("s_waitcnt vmcnt(%0)" :: "n"(n) : "memory")
; #define A2_BAR() do { __builtin_amdgcn_s_barrier(); asm volatile("" ::: "memory"); } while (0)
; template <int TYPE>
; __device__ __forceinline__ void attn_mfma_unit2(const AttnCtx& A, unsigned char* ws, LAS unsigned char* lds, int tid, const AUnit& u) {
;     ...
;             A2_WAITN(0); A2_BAR();
;             sprv = scur; scur = snxt; snxt = snxt == 2 * STG ? 0 : snxt + STG;
	v_mfma_f32_32x32x16_bf16 v[64:79], v[6:9], v[2:5], v[64:79]
	v_mfma_f32_32x32x16_bf16 v[48:63], v[10:13], v[2:5], v[48:63]
	v_mfma_f32_32x32x16_bf16 v[32:47], v[96:99], v[2:5], v[32:47]
	v_mfma_f32_32x32x16_bf16 v[16:31], v[104:107], v[2:5], v[16:31]
	v_exp_f32_e32 v142, v88
	v_exp_f32_e32 v144, v89
	v_exp_f32_e32 v146, v90
	v_exp_f32_e32 v148, v91
	v_exp_f32_e32 v14, v92
	v_exp_f32_e32 v140, v93
	v_exp_f32_e32 v156, v94
	v_exp_f32_e32 v0, v95
	v_cvt_pk_bf16_f32 v2, v142, v144
	v_cvt_pk_bf16_f32 v3, v146, v148
	v_cvt_pk_bf16_f32 v4, v14, v140
	v_cvt_pk_bf16_f32 v5, v156, v0
	s_nop 1
	v_mfma_f32_32x32x16_bf16 v[64:79], v[80:83], v[2:5], v[64:79]
	v_add_f32_e64 v6, v142, v144
	v_add_f32_e64 v7, v143, v145
	v_add_f32_e64 v8, v146, v148
	v_add_f32_e64 v9, v147, v149
	v_add_f32_e64 v10, v156, v0
	v_add_f32_e64 v11, v157, v1
	v_pk_add_f32 v[6:7], v[6:7], v[8:9]
	v_pk_add_f32 v[8:9], v[14:15], v[140:141]
	s_nop 0
	v_pk_add_f32 v[8:9], v[8:9], v[10:11]
	v_mfma_f32_32x32x16_bf16 v[48:63], v[84:87], v[2:5], v[48:63]
	v_add_f32_e64 v6, v6, v8
	v_add_f32_e64 v7, v7, v9
	v_pk_add_f32 v[6:7], v[6:7], v[6:7] op_sel:[0,1] op_sel_hi:[1,0]
	v_mfma_f32_32x32x16_bf16 v[32:47], v[100:103], v[2:5], v[32:47]
	v_mfma_f32_32x32x16_bf16 v[16:31], v[108:111], v[2:5], v[16:31]
	v_mov_b32_e32 v0, v6
	s_nop 1
	v_permlane32_swap_b32_e32 v6, v0
	v_add_f32_e32 v0, v6, v0
	v_add_f32_e32 v139, v139, v0
	v_add_u32_e32 v0, s7, v137
	ds_read_b128 v[2:5], v0
	ds_read_b128 v[6:9], v0 offset:4096
	v_add_u32_e32 v0, s7, v136
	ds_read_b128 v[10:13], v0
	ds_read_b128 v[140:143], v0 offset:4096
	v_add_u32_e32 v0, s7, v135
	v_add_u32_e32 v14, s7, v134
	ds_read_b128 v[144:147], v0
	ds_read_b128 v[148:151], v0 offset:4096
	ds_read_b128 v[152:155], v14
	ds_read_b128 v[156:159], v14 offset:4096
	v_xor_b32_e32 v80, 0x80000000, v138
	v_mov_b32_e32 v81, v80
	v_mov_b32_e32 v82, v80
	v_mov_b32_e32 v83, v80
	v_mov_b32_e32 v84, v80
	v_mov_b32_e32 v85, v80
	v_mov_b32_e32 v86, v80
	v_mov_b32_e32 v87, v80
	v_mov_b32_e32 v88, v80
	v_mov_b32_e32 v89, v80
	v_mov_b32_e32 v90, v80
	v_mov_b32_e32 v91, v80
	v_mov_b32_e32 v92, v80
	v_mov_b32_e32 v93, v80
	v_mov_b32_e32 v94, v80
	v_mov_b32_e32 v95, v80
	s_waitcnt lgkmcnt(0)
	s_nop 0
	v_mfma_f32_32x32x16_bf16 v[96:111], v[2:5], v[124:127], v[80:95]
	v_mfma_f32_32x32x16_bf16 v[96:111], v[10:13], v[120:123], v[96:111]
	v_mfma_f32_32x32x16_bf16 v[96:111], v[144:147], v[116:119], v[96:111]
	v_mfma_f32_32x32x16_bf16 v[96:111], v[152:155], v[112:115], v[96:111]
	v_mfma_f32_32x32x16_bf16 v[80:95], v[6:9], v[124:127], v[80:95]
	s_nop 10
	v_max_f32_e32 v0, v97, v97
	v_max_f32_e32 v2, v96, v96
	v_max_f32_e32 v0, v2, v0
	v_max3_f32 v0, v0, v98, v99
	v_max3_f32 v0, v0, v100, v101
	v_max3_f32 v0, v0, v102, v103
	v_max3_f32 v0, v0, v104, v105
	v_mfma_f32_32x32x16_bf16 v[80:95], v[140:143], v[120:123], v[80:95]
	v_max3_f32 v0, v0, v106, v107
	v_max3_f32 v0, v0, v108, v109
	v_max3_f32 v0, v0, v110, v111
	s_mov_b32 s47, 0x41000000
	v_mfma_f32_32x32x16_bf16 v[80:95], v[148:151], v[116:119], v[80:95]
	v_mfma_f32_32x32x16_bf16 v[80:95], v[156:159], v[112:115], v[80:95]
	s_nop 11
	v_max3_f32 v0, v0, v80, v81
	v_max3_f32 v0, v0, v82, v83
	v_max3_f32 v0, v0, v84, v85
	v_max3_f32 v0, v0, v86, v87
	v_max3_f32 v0, v0, v88, v89
	v_max3_f32 v0, v0, v90, v91
	v_max3_f32 v0, v0, v92, v93
	v_max3_f32 v0, v0, v94, v95
	v_mov_b32_e32 v2, v0
	s_nop 1
	v_permlane32_swap_b32_e32 v0, v2
	v_max_f32_e32 v2, v2, v2
	v_max_f32_e32 v0, v0, v0
	v_max_f32_e32 v0, v0, v2
	v_cmp_ge_f32_e32 vcc, s47, v0
	s_cmp_eq_u64 vcc, exec
	s_cbranch_scc1 .LBB0_2783
	v_max_f32_e32 v0, v0, v0
	v_max_f32_e32 v2, 0, v0
	v_exp_f32_e64 v0, -v2
	v_add_f32_e32 v138, v138, v2
	v_sub_f32_e32 v111, v111, v2
	v_sub_f32_e32 v110, v110, v2
	v_pk_mul_f32 v[78:79], v[78:79], v[0:1] op_sel_hi:[1,0]
	v_pk_mul_f32 v[76:77], v[76:77], v[0:1] op_sel_hi:[1,0]
	v_pk_mul_f32 v[74:75], v[74:75], v[0:1] op_sel_hi:[1,0]
	v_pk_mul_f32 v[72:73], v[72:73], v[0:1] op_sel_hi:[1,0]
	v_pk_mul_f32 v[70:71], v[70:71], v[0:1] op_sel_hi:[1,0]
	v_pk_mul_f32 v[68:69], v[68:69], v[0:1] op_sel_hi:[1,0]
	v_pk_mul_f32 v[66:67], v[66:67], v[0:1] op_sel_hi:[1,0]
	v_pk_mul_f32 v[64:65], v[64:65], v[0:1] op_sel_hi:[1,0]
	v_pk_mul_f32 v[62:63], v[62:63], v[0:1] op_sel_hi:[1,0]
	v_pk_mul_f32 v[60:61], v[60:61], v[0:1] op_sel_hi:[1,0]
	v_pk_mul_f32 v[58:59], v[58:59], v[0:1] op_sel_hi:[1,0]
	v_pk_mul_f32 v[56:57], v[56:57], v[0:1] op_sel_hi:[1,0]
	v_pk_mul_f32 v[54:55], v[54:55], v[0:1] op_sel_hi:[1,0]
	v_pk_mul_f32 v[52:53], v[52:53], v[0:1] op_sel_hi:[1,0]
	v_pk_mul_f32 v[50:51], v[50:51], v[0:1] op_sel_hi:[1,0]
	v_pk_mul_f32 v[48:49], v[48:49], v[0:1] op_sel_hi:[1,0]
	v_pk_mul_f32 v[46:47], v[46:47], v[0:1] op_sel_hi:[1,0]
	v_pk_mul_f32 v[44:45], v[44:45], v[0:1] op_sel_hi:[1,0]
	v_pk_mul_f32 v[42:43], v[42:43], v[0:1] op_sel_hi:[1,0]
	v_pk_mul_f32 v[40:41], v[40:41], v[0:1] op_sel_hi:[1,0]
	v_pk_mul_f32 v[38:39], v[38:39], v[0:1] op_sel_hi:[1,0]
	v_pk_mul_f32 v[36:37], v[36:37], v[0:1] op_sel_hi:[1,0]
	v_pk_mul_f32 v[34:35], v[34:35], v[0:1] op_sel_hi:[1,0]
	v_pk_mul_f32 v[32:33], v[32:33], v[0:1] op_sel_hi:[1,0]
	v_pk_mul_f32 v[30:31], v[30:31], v[0:1] op_sel_hi:[1,0]
	v_pk_mul_f32 v[28:29], v[28:29], v[0:1] op_sel_hi:[1,0]
	v_pk_mul_f32 v[26:27], v[26:27], v[0:1] op_sel_hi:[1,0]
	v_pk_mul_f32 v[24:25], v[24:25], v[0:1] op_sel_hi:[1,0]
	v_pk_mul_f32 v[22:23], v[22:23], v[0:1] op_sel_hi:[1,0]
	v_pk_mul_f32 v[20:21], v[20:21], v[0:1] op_sel_hi:[1,0]
	v_pk_mul_f32 v[18:19], v[18:19], v[0:1] op_sel_hi:[1,0]
	v_pk_mul_f32 v[16:17], v[16:17], v[0:1] op_sel_hi:[1,0]
	v_sub_f32_e32 v109, v109, v2
	v_sub_f32_e32 v108, v108, v2
	v_sub_f32_e32 v107, v107, v2
	v_sub_f32_e32 v106, v106, v2
	v_sub_f32_e32 v105, v105, v2
	v_sub_f32_e32 v104, v104, v2
	v_sub_f32_e32 v103, v103, v2
	v_sub_f32_e32 v102, v102, v2
	v_sub_f32_e32 v101, v101, v2
	v_sub_f32_e32 v100, v100, v2
	v_sub_f32_e32 v99, v99, v2
	v_sub_f32_e32 v98, v98, v2
	v_sub_f32_e32 v97, v97, v2
	v_sub_f32_e32 v96, v96, v2
	v_sub_f32_e32 v95, v95, v2
	v_sub_f32_e32 v94, v94, v2
	v_sub_f32_e32 v93, v93, v2
	v_sub_f32_e32 v92, v92, v2
	v_sub_f32_e32 v91, v91, v2
	v_sub_f32_e32 v90, v90, v2
	v_sub_f32_e32 v89, v89, v2
	v_sub_f32_e32 v88, v88, v2
	v_sub_f32_e32 v87, v87, v2
	v_sub_f32_e32 v86, v86, v2
	v_sub_f32_e32 v85, v85, v2
	v_sub_f32_e32 v84, v84, v2
	v_sub_f32_e32 v83, v83, v2
	v_sub_f32_e32 v82, v82, v2
	v_sub_f32_e32 v81, v81, v2
	v_sub_f32_e32 v80, v80, v2
	v_mul_f32_e32 v139, v139, v0
.LBB0_2783:
	v_add_u32_e32 v0, s7, v137
	ds_read_b128 v[2:5], v0 offset:8192
	ds_read_b128 v[6:9], v0 offset:12288
	ds_read_b128 v[10:13], v0 offset:16384
	ds_read_b128 v[140:143], v0 offset:20480
	s_waitcnt vmcnt(0)
	s_barrier
	s_add_i32 s47, s6, 0x6000
	s_cmpk_lg_u32 s6, 0xc000
	s_cselect_b32 s48, s47, 0
	s_cmp_lg_u32 s15, s45
	s_cbranch_scc0 .LBB0_2788
	s_mov_b32 s47, s6
	s_mov_b32 s6, s48
	s_mov_b32 s15, s46
	s_branch .LBB0_2781

; #define A2_WAITN(n) asm volatile("s_waitcnt vmcnt(%0)" :: "n"(n) : "memory")
; #define A2_BAR() do { __builtin_amdgcn_s_barrier(); asm volatile("" ::: "memory"); } while (0)
; #define A2_SETKC(SOFF) _Pragma("unroll") for (int _i = 0; _i < NKB; ++_i) kc[_i] = kbase[_i] + (unsigned)(SOFF)
; #define A2_SETVC(SOFF) _Pragma("unroll") for (int _i = 0; _i < 4; ++_i) vc[_i] = vbase[_i] + (unsigned)(SOFF)
; template <int TYPE>
; __device__ __forceinline__ void attn_mfma_unit2(const AttnCtx& A, unsigned char* ws, LAS unsigned char* lds, int tid, const AUnit& u) {
;     ...
;         for (int ti = 0; ti < nt; ++ti) {
;             if (ti + 1 < nt) A2_DMA(ti + 1, snxt);
;             if (actP) { A2_SETVC(sprv); A2_FSM_PV(sA0, sA1, 0); }
;             actP = A2_ACTIVE(ti);
;             if (actP) { A2_SETKC(scur); A2_QK(sA0, sA1, ti, 0); A2_PSM(sA0, sA1); }
;             A2_WAITN(0); A2_BAR();
;             sprv = scur; scur = snxt; snxt = snxt == 2 * STG ? 0 : snxt + STG;
;         }
;         if (actP) { A2_SETVC(sprv); A2_FSM_PV(sA0, sA1, 0); }
.LBB0_2788:
	s_waitcnt lgkmcnt(0)
	v_add_u32_e32 v0, s7, v137
	ds_read_b128 v[2:5], v0 offset:8192
	ds_read_b128 v[6:9], v0 offset:12288
	ds_read_b128 v[10:13], v0 offset:16384
	ds_read_b128 v[128:131], v0 offset:20480
	v_exp_f32_e32 v14, v96
	v_exp_f32_e32 v132, v97
	v_exp_f32_e32 v98, v98
	v_exp_f32_e32 v140, v99
	v_exp_f32_e32 v15, v100
	v_exp_f32_e32 v133, v101
	v_exp_f32_e32 v99, v102
	v_exp_f32_e32 v141, v103
	v_add_u32_e32 v0, s7, v136
	v_pk_add_f32 v[96:97], v[14:15], v[132:133]
	v_pk_add_f32 v[100:101], v[98:99], v[140:141]
	s_nop 0
	v_pk_add_f32 v[96:97], v[96:97], v[100:101]
	v_cvt_pk_bf16_f32 v99, v99, v141
	v_pk_add_f32 v[152:153], v[96:97], v[96:97] op_sel_hi:[0,1]
	v_cvt_pk_bf16_f32 v97, v98, v140
	ds_read_b128 v[100:103], v0 offset:8192
	ds_read_b128 v[140:143], v0 offset:12288
	ds_read_b128 v[144:147], v0 offset:16384
	ds_read_b128 v[148:151], v0 offset:20480
	v_cvt_pk_bf16_f32 v96, v14, v132
	v_cvt_pk_bf16_f32 v98, v15, v133
	s_waitcnt lgkmcnt(0)
	s_nop 0
	v_mfma_f32_32x32x16_bf16 v[64:79], v[2:5], v[96:99], v[64:79]
	v_mfma_f32_32x32x16_bf16 v[48:63], v[6:9], v[96:99], v[48:63]
	v_mfma_f32_32x32x16_bf16 v[32:47], v[10:13], v[96:99], v[32:47]
	v_mfma_f32_32x32x16_bf16 v[16:31], v[128:131], v[96:99], v[16:31]
	v_exp_f32_e32 v2, v104
	v_exp_f32_e32 v4, v105
	v_exp_f32_e32 v3, v106
	v_exp_f32_e32 v5, v107
	v_exp_f32_e32 v6, v108
	v_exp_f32_e32 v8, v109
	v_exp_f32_e32 v7, v110
	v_exp_f32_e32 v9, v111
	v_pk_add_f32 v[10:11], v[2:3], v[4:5]
	v_add_u32_e32 v0, s7, v135
	v_pk_add_f32 v[14:15], v[10:11], v[10:11] op_sel_hi:[0,1]
	v_pk_add_f32 v[10:11], v[6:7], v[8:9]
	v_cvt_pk_bf16_f32 v2, v2, v4
	v_pk_add_f32 v[128:129], v[10:11], v[10:11] op_sel_hi:[0,1]
	v_cvt_pk_bf16_f32 v3, v3, v5
	v_cvt_pk_bf16_f32 v4, v6, v8
	v_cvt_pk_bf16_f32 v5, v7, v9
	ds_read_b128 v[6:9], v0 offset:8192
	ds_read_b128 v[10:13], v0 offset:12288
	ds_read_b128 v[96:99], v0 offset:16384
	ds_read_b128 v[104:107], v0 offset:20480
	v_mfma_f32_32x32x16_bf16 v[64:79], v[100:103], v[2:5], v[64:79]
	v_mfma_f32_32x32x16_bf16 v[48:63], v[140:143], v[2:5], v[48:63]
	v_mfma_f32_32x32x16_bf16 v[32:47], v[144:147], v[2:5], v[32:47]
	v_mfma_f32_32x32x16_bf16 v[16:31], v[148:151], v[2:5], v[16:31]
	v_exp_f32_e32 v0, v80
	v_exp_f32_e32 v2, v81
	v_exp_f32_e32 v3, v82
	v_exp_f32_e32 v4, v83
	v_exp_f32_e32 v5, v84
	v_exp_f32_e32 v14, v85
	v_exp_f32_e32 v80, v86
	v_exp_f32_e32 v81, v87
	v_add_f32_e32 v131, v0, v2
	v_cvt_pk_bf16_f32 v2, v0, v2
	v_add_u32_e32 v0, s7, v134
	v_add_f32_e32 v133, v3, v4
	v_add_f32_e32 v141, v5, v14
	v_add_f32_e32 v143, v80, v81
	v_cvt_pk_bf16_f32 v3, v3, v4
	v_cvt_pk_bf16_f32 v4, v5, v14
	v_cvt_pk_bf16_f32 v5, v80, v81
	ds_read_b128 v[80:83], v0 offset:8192
	ds_read_b128 v[84:87], v0 offset:12288
	ds_read_b128 v[100:103], v0 offset:16384
	ds_read_b128 v[108:111], v0 offset:20480
	s_waitcnt lgkmcnt(0)
	v_mfma_f32_32x32x16_bf16 v[64:79], v[6:9], v[2:5], v[64:79]
	v_mfma_f32_32x32x16_bf16 v[48:63], v[10:13], v[2:5], v[48:63]
	v_mfma_f32_32x32x16_bf16 v[32:47], v[96:99], v[2:5], v[32:47]
	v_mfma_f32_32x32x16_bf16 v[16:31], v[104:107], v[2:5], v[16:31]
	v_exp_f32_e32 v130, v88
	v_exp_f32_e32 v132, v89
	v_exp_f32_e32 v140, v90
	v_exp_f32_e32 v142, v91
	v_exp_f32_e32 v14, v92
	v_exp_f32_e32 v128, v93
	v_exp_f32_e32 v152, v94
	v_exp_f32_e32 v0, v95
	v_cvt_pk_bf16_f32 v2, v130, v132
	v_cvt_pk_bf16_f32 v3, v140, v142
	v_cvt_pk_bf16_f32 v4, v14, v128
	v_cvt_pk_bf16_f32 v5, v152, v0
	s_nop 1
	v_mfma_f32_32x32x16_bf16 v[64:79], v[80:83], v[2:5], v[64:79]
	v_add_f32_e64 v6, v130, v132
	v_add_f32_e64 v7, v131, v133
	v_add_f32_e64 v8, v140, v142
	v_add_f32_e64 v9, v141, v143
	v_add_f32_e64 v10, v152, v0
	v_add_f32_e64 v11, v153, v1
	v_pk_add_f32 v[6:7], v[6:7], v[8:9]
	v_pk_add_f32 v[8:9], v[14:15], v[128:129]
	s_nop 0
	v_pk_add_f32 v[8:9], v[8:9], v[10:11]
	v_mfma_f32_32x32x16_bf16 v[48:63], v[84:87], v[2:5], v[48:63]
	v_add_f32_e64 v6, v6, v8
	v_add_f32_e64 v7, v7, v9
	v_pk_add_f32 v[6:7], v[6:7], v[6:7] op_sel:[0,1] op_sel_hi:[1,0]
	v_mfma_f32_32x32x16_bf16 v[32:47], v[100:103], v[2:5], v[32:47]
	v_mfma_f32_32x32x16_bf16 v[16:31], v[108:111], v[2:5], v[16:31]
	v_mov_b32_e32 v0, v6
	s_nop 1
	v_permlane32_swap_b32_e32 v6, v0
	v_add_f32_e32 v0, v6, v0
	v_add_u32_e32 v5, s6, v137
	v_add_u32_e32 v4, s6, v136
	v_add_u32_e32 v3, s6, v135
	v_add_f32_e32 v2, v139, v0
	v_xor_b32_e32 v80, 0x80000000, v138
	ds_read_b128 v[6:9], v5
	ds_read_b128 v[10:13], v5 offset:4096
	ds_read_b128 v[128:131], v4
	ds_read_b128 v[136:139], v4 offset:4096
	v_add_u32_e32 v0, s6, v134
	ds_read_b128 v[132:135], v3
	ds_read_b128 v[140:143], v3 offset:4096
	ds_read_b128 v[144:147], v0
	ds_read_b128 v[148:151], v0 offset:4096
	v_mov_b32_e32 v81, v80
	v_mov_b32_e32 v82, v80
	v_mov_b32_e32 v83, v80
	v_mov_b32_e32 v84, v80
	v_mov_b32_e32 v85, v80
	v_mov_b32_e32 v86, v80
	v_mov_b32_e32 v87, v80
	v_mov_b32_e32 v88, v80
	v_mov_b32_e32 v89, v80
	v_mov_b32_e32 v90, v80
	v_mov_b32_e32 v91, v80
	v_mov_b32_e32 v92, v80
	v_mov_b32_e32 v93, v80
	v_mov_b32_e32 v94, v80
	v_mov_b32_e32 v95, v80
	s_waitcnt lgkmcnt(0)
	s_nop 0
	v_mfma_f32_32x32x16_bf16 v[96:111], v[6:9], v[124:127], v[80:95]
	v_mfma_f32_32x32x16_bf16 v[96:111], v[128:131], v[120:123], v[96:111]
	v_mfma_f32_32x32x16_bf16 v[96:111], v[132:135], v[116:119], v[96:111]
	v_mfma_f32_32x32x16_bf16 v[96:111], v[144:147], v[112:115], v[96:111]
	v_mfma_f32_32x32x16_bf16 v[80:95], v[10:13], v[124:127], v[80:95]
	s_nop 10
	v_max_f32_e32 v6, v97, v97
	v_max_f32_e32 v7, v96, v96
	v_max_f32_e32 v6, v7, v6
	v_max3_f32 v6, v6, v98, v99
	v_max3_f32 v6, v6, v100, v101
	v_max3_f32 v6, v6, v102, v103
	v_max3_f32 v6, v6, v104, v105
	v_mfma_f32_32x32x16_bf16 v[80:95], v[136:139], v[120:123], v[80:95]
	v_max3_f32 v6, v6, v106, v107
	v_max3_f32 v6, v6, v108, v109
	v_max3_f32 v6, v6, v110, v111
	s_mov_b32 s6, 0x41000000
	v_mfma_f32_32x32x16_bf16 v[80:95], v[140:143], v[116:119], v[80:95]
	v_mfma_f32_32x32x16_bf16 v[80:95], v[148:151], v[112:115], v[80:95]
	s_nop 11
	v_max3_f32 v6, v6, v80, v81
	v_max3_f32 v6, v6, v82, v83
	v_max3_f32 v6, v6, v84, v85
	v_max3_f32 v6, v6, v86, v87
	v_max3_f32 v6, v6, v88, v89
	v_max3_f32 v6, v6, v90, v91
	v_max3_f32 v6, v6, v92, v93
	v_max3_f32 v6, v6, v94, v95
	v_mov_b32_e32 v7, v6
	s_nop 1
	v_permlane32_swap_b32_e32 v6, v7
	v_max_f32_e32 v7, v7, v7
	v_max_f32_e32 v6, v6, v6
	v_max_f32_e32 v6, v6, v7
	v_cmp_ge_f32_e32 vcc, s6, v6
	s_cmp_eq_u64 vcc, exec
	s_cbranch_scc1 .LBB0_2790
	v_max_f32_e32 v6, v6, v6
	v_max_f32_e32 v6, 0, v6
	v_exp_f32_e64 v8, -v6
	v_pk_add_f32 v[96:97], v[96:97], v[6:7] op_sel_hi:[1,0] neg_lo:[0,1] neg_hi:[0,1]
	v_pk_add_f32 v[80:81], v[80:81], v[6:7] op_sel_hi:[1,0] neg_lo:[0,1] neg_hi:[0,1]
	v_pk_add_f32 v[98:99], v[98:99], v[6:7] op_sel_hi:[1,0] neg_lo:[0,1] neg_hi:[0,1]
	v_pk_mul_f32 v[78:79], v[78:79], v[8:9] op_sel_hi:[1,0]
	v_pk_mul_f32 v[76:77], v[76:77], v[8:9] op_sel_hi:[1,0]
	v_pk_mul_f32 v[74:75], v[74:75], v[8:9] op_sel_hi:[1,0]
	v_pk_mul_f32 v[72:73], v[72:73], v[8:9] op_sel_hi:[1,0]
	v_pk_mul_f32 v[70:71], v[70:71], v[8:9] op_sel_hi:[1,0]
	v_pk_mul_f32 v[68:69], v[68:69], v[8:9] op_sel_hi:[1,0]
	v_pk_mul_f32 v[66:67], v[66:67], v[8:9] op_sel_hi:[1,0]
	v_pk_mul_f32 v[64:65], v[64:65], v[8:9] op_sel_hi:[1,0]
	v_pk_mul_f32 v[62:63], v[62:63], v[8:9] op_sel_hi:[1,0]
	v_pk_mul_f32 v[60:61], v[60:61], v[8:9] op_sel_hi:[1,0]
	v_pk_mul_f32 v[58:59], v[58:59], v[8:9] op_sel_hi:[1,0]
	v_pk_mul_f32 v[56:57], v[56:57], v[8:9] op_sel_hi:[1,0]
	v_pk_mul_f32 v[54:55], v[54:55], v[8:9] op_sel_hi:[1,0]
	v_pk_mul_f32 v[52:53], v[52:53], v[8:9] op_sel_hi:[1,0]
	v_pk_mul_f32 v[50:51], v[50:51], v[8:9] op_sel_hi:[1,0]
	v_pk_mul_f32 v[48:49], v[48:49], v[8:9] op_sel_hi:[1,0]
	v_pk_mul_f32 v[46:47], v[46:47], v[8:9] op_sel_hi:[1,0]
	v_pk_mul_f32 v[44:45], v[44:45], v[8:9] op_sel_hi:[1,0]
	v_pk_mul_f32 v[42:43], v[42:43], v[8:9] op_sel_hi:[1,0]
	v_pk_mul_f32 v[40:41], v[40:41], v[8:9] op_sel_hi:[1,0]
	v_pk_mul_f32 v[38:39], v[38:39], v[8:9] op_sel_hi:[1,0]
	v_pk_mul_f32 v[36:37], v[36:37], v[8:9] op_sel_hi:[1,0]
	v_pk_mul_f32 v[34:35], v[34:35], v[8:9] op_sel_hi:[1,0]
	v_pk_mul_f32 v[32:33], v[32:33], v[8:9] op_sel_hi:[1,0]
	v_pk_mul_f32 v[30:31], v[30:31], v[8:9] op_sel_hi:[1,0]
	v_pk_mul_f32 v[28:29], v[28:29], v[8:9] op_sel_hi:[1,0]
	v_pk_mul_f32 v[26:27], v[26:27], v[8:9] op_sel_hi:[1,0]
	v_pk_mul_f32 v[24:25], v[24:25], v[8:9] op_sel_hi:[1,0]
	v_pk_mul_f32 v[22:23], v[22:23], v[8:9] op_sel_hi:[1,0]
	v_pk_mul_f32 v[20:21], v[20:21], v[8:9] op_sel_hi:[1,0]
	v_pk_mul_f32 v[18:19], v[18:19], v[8:9] op_sel_hi:[1,0]
	v_pk_mul_f32 v[16:17], v[16:17], v[8:9] op_sel_hi:[1,0]
	v_pk_add_f32 v[82:83], v[82:83], v[6:7] op_sel_hi:[1,0] neg_lo:[0,1] neg_hi:[0,1]
	v_pk_add_f32 v[100:101], v[100:101], v[6:7] op_sel_hi:[1,0] neg_lo:[0,1] neg_hi:[0,1]
	v_pk_add_f32 v[84:85], v[84:85], v[6:7] op_sel_hi:[1,0] neg_lo:[0,1] neg_hi:[0,1]
	v_pk_add_f32 v[102:103], v[102:103], v[6:7] op_sel_hi:[1,0] neg_lo:[0,1] neg_hi:[0,1]
	v_pk_add_f32 v[86:87], v[86:87], v[6:7] op_sel_hi:[1,0] neg_lo:[0,1] neg_hi:[0,1]
	v_pk_add_f32 v[104:105], v[104:105], v[6:7] op_sel_hi:[1,0] neg_lo:[0,1] neg_hi:[0,1]
	v_pk_add_f32 v[88:89], v[88:89], v[6:7] op_sel_hi:[1,0] neg_lo:[0,1] neg_hi:[0,1]
	v_pk_add_f32 v[106:107], v[106:107], v[6:7] op_sel_hi:[1,0] neg_lo:[0,1] neg_hi:[0,1]
	v_pk_add_f32 v[90:91], v[90:91], v[6:7] op_sel_hi:[1,0] neg_lo:[0,1] neg_hi:[0,1]
	v_pk_add_f32 v[108:109], v[108:109], v[6:7] op_sel_hi:[1,0] neg_lo:[0,1] neg_hi:[0,1]
	v_pk_add_f32 v[92:93], v[92:93], v[6:7] op_sel_hi:[1,0] neg_lo:[0,1] neg_hi:[0,1]
	v_pk_add_f32 v[110:111], v[110:111], v[6:7] op_sel_hi:[1,0] neg_lo:[0,1] neg_hi:[0,1]
	v_pk_add_f32 v[94:95], v[94:95], v[6:7] op_sel_hi:[1,0] neg_lo:[0,1] neg_hi:[0,1]
	v_mul_f32_e32 v2, v2, v8

; #define LAS __attribute__((address_space(3)))
; __device__ __forceinline__ int swap23(int k) { return (k & ~12) | ((k & 4) << 1) | ((k & 8) >> 1); }
; #define A2_WAITN(n) asm volatile("s_waitcnt vmcnt(%0)" :: "n"(n) : "memory")
; template <int TYPE>
; __device__ __forceinline__ void attn_mfma_unit2(const AttnCtx& A, unsigned char* ws, LAS unsigned char* lds, int tid, const AUnit& u) {
;     ...
;     const int w = __builtin_amdgcn_readfirstlane(tid >> 6), lane = tid & 63, q = lane & 31, h2 = lane >> 5;
;     const bf16_t* Qg; const bf16_t* Kg; const bf16_t* VTg; int ld;
;     if (TYPE == 0) { Qg = A.naq + u.h * 128; Kg = A.nak + u.h * 128; ld = 768; VTg = A.vtin + (size_t)(u.h * 128) * M; }
;     else if (TYPE == 1) { Qg = A.mq + u.h * 192; Kg = A.mk + u.h * 192; ld = 960; VTg = A.vtm + (size_t)(u.h * 128) * M; }
;     else { Qg = A.dq + u.h * 128 + 64 * u.pass; Kg = A.dk + u.h * 128 + 64 * u.pass; ld = 640; VTg = A.vtin + (size_t)(768 + u.h * 128) * M; }
;     ...
;     if (w < 4) __builtin_amdgcn_s_setprio(2); else __builtin_amdgcn_s_setprio(0);
;     ...
;     const int qrow = u.qrow0 + 32 * w + q;
;     bf16x8 qf[NKK];
; #pragma unroll
;     for (int kk = 0; kk < NKK; ++kk) qf[kk] = *(const bf16x8*)(Qg + (size_t)qrow * ld + 16 * kk + 8 * h2);
;     int lo = 0, nlat = u.isctx ? 0 : 64, qr = 0, qc = 0, r0w = 0, c0 = 0;
;     if (TYPE == 0 && !u.isctx) {
;         int a = 4 * u.g - 4; lo = a < 0 ? 0 : (a > 56 ? 56 : a); int hb = 4 * u.g + 3 - 4; hb = hb < 0 ? 0 : (hb > 56 ? 56 : hb); nlat = hb + 8 - lo;
;         qr = 4 * u.g + (w >> 1); qc = 32 * (w & 1) + q; int t = qr - 4; r0w = t < 0 ? 0 : (t > 56 ? 56 : t); t = qc - 8; c0 = t < 0 ? 0 : (t > 48 ? 48 : t);
;         LAS float* rp = (LAS float*)(lds + A2_RPB);
;         if (tid < 465) rp[tid] = A.rpb[u.h * 465 + tid] * LOG2E;
;     }
;     const int nt = 4 + nlat;
;     unsigned goff[NIW];
; #pragma unroll
;     for (int m = 0; m < NIW; ++m) {
;         if (m < NIK) { const int p = 64 * (w + 8 * m) + lane, row = p / NKC, slot = p % NKC; const int c = DQK == 128 ? (slot ^ (row & 15)) : (slot ^ ((row >> 1) & 7)); goff[m] = (unsigned)(swap23(row) * ld + 8 * c); }
;         else { const int p = 64 * (w + 8 * (m - NIK)) + lane, ch = p >> 3, slot = p & 7; const int c = slot ^ ((ch >> 1) & 7); goff[m] = (unsigned)(ch * M + 8 * c); }
;     ...
;     A2_DMA(0, 0);
;     asm volatile("s_waitcnt lgkmcnt(0)" ::: "memory");
;     A2_WAITN(0); A2_BAR();
.LBB0_2901:
	s_mul_i32 s2, s16, 0xc0
	s_ashr_i32 s3, s2, 31
	s_lshl_b64 s[2:3], s[2:3], 1
	s_add_u32 s14, s26, s2
	s_addc_u32 s15, s27, s3
	s_add_u32 s7, s90, s2
	s_addc_u32 s8, s91, s3
	s_lshl_b32 s2, s16, 7
	s_ashr_i32 s3, s2, 31
	s_mul_i32 s6, s16, 0x220000
	s_mul_hi_i32 s10, s2, 0x4400
	s_add_u32 s9, s92, s6
	s_addc_u32 s10, s93, s10
	s_lshl_b32 s6, s12, 5
	v_and_b32_e32 v16, 31, v2
	s_add_i32 s6, s6, s19
	v_bfe_u32 v17, v2, 5, 1
	v_add_u32_e32 v0, s6, v16
	v_mov_b64_e32 v[4:5], s[14:15]
	s_movk_i32 s13, 0x780
	v_mad_i64_i32 v[4:5], s[14:15], v0, s13, v[4:5]
	v_lshlrev_b32_e32 v0, 4, v17
	v_lshl_add_u64 v[4:5], v[4:5], 0, v[0:1]
	s_and_b32 s13, s11, 0xffffffc0
	v_mov_b32_e32 v0, s11
	s_movk_i32 s11, 0xffc0
	v_bfi_b32 v0, s11, v0, v2
	s_mov_b32 s14, 0x2aaaaaab
	global_load_dwordx4 v[112:115], v[4:5], off
	global_load_dwordx4 v[116:119], v[4:5], off offset:32
	global_load_dwordx4 v[120:123], v[4:5], off offset:64
	global_load_dwordx4 v[124:127], v[4:5], off offset:96
	global_load_dwordx4 v[128:131], v[4:5], off offset:128
	global_load_dwordx4 v[132:135], v[4:5], off offset:160
	global_load_dwordx4 v[136:139], v[4:5], off offset:192
	global_load_dwordx4 v[140:143], v[4:5], off offset:224
	global_load_dwordx4 v[144:147], v[4:5], off offset:256
	global_load_dwordx4 v[148:151], v[4:5], off offset:288
	global_load_dwordx4 v[152:155], v[4:5], off offset:320
	global_load_dwordx4 v[156:159], v[4:5], off offset:352
	v_mul_hi_i32 v4, v0, s14
	v_lshrrev_b32_e32 v5, 31, v4
	v_ashrrev_i32_e32 v4, 2, v4
	v_add_u32_e32 v4, v4, v5
	v_mul_lo_u32 v5, v4, 24
	v_sub_u32_e32 v5, v0, v5
	v_lshrrev_b32_e32 v6, 1, v4
	v_and_b32_e32 v7, 0x3fffff3, v4
	v_lshlrev_b32_e32 v4, 1, v4
	v_bitop3_b32 v5, v6, v5, 7 bitop3:0x6c
	v_and_b32_e32 v4, 8, v4
	v_and_b32_e32 v6, 4, v6
	v_or3_b32 v4, v7, v4, v6
	s_movk_i32 s11, 0x3c0
	v_mul_lo_u32 v4, v4, s11
	s_waitcnt vmcnt(0)
	v_lshl_add_u32 v160, v5, 3, v4
	v_add_u32_e32 v4, 0x200, v0
	v_mul_hi_i32 v5, v4, s14
	v_lshrrev_b32_e32 v6, 31, v5
	v_ashrrev_i32_e32 v5, 2, v5
	v_add_u32_e32 v5, v5, v6
	v_mul_lo_u32 v6, v5, 24
	v_sub_u32_e32 v4, v4, v6
	v_lshrrev_b32_e32 v6, 1, v5
	v_and_b32_e32 v7, 0x3fffff3, v5
	v_lshlrev_b32_e32 v5, 1, v5
	v_bitop3_b32 v4, v6, v4, 7 bitop3:0x6c
	v_and_b32_e32 v5, 8, v5
	v_and_b32_e32 v6, 4, v6
	v_or3_b32 v5, v7, v5, v6
	v_mul_lo_u32 v5, v5, s11
	v_lshl_add_u32 v162, v4, 3, v5
	v_add_u32_e32 v4, 0x400, v0
	v_mul_hi_i32 v5, v4, s14
	v_lshrrev_b32_e32 v6, 31, v5
	v_ashrrev_i32_e32 v5, 2, v5
	v_add_u32_e32 v5, v5, v6
	v_mul_lo_u32 v6, v5, 24
	v_sub_u32_e32 v4, v4, v6
	v_lshrrev_b32_e32 v6, 1, v5
	v_and_b32_e32 v7, 0x3fffff3, v5
	v_lshlrev_b32_e32 v5, 1, v5
	v_bitop3_b32 v4, v6, v4, 7 bitop3:0x6c
	v_and_b32_e32 v5, 8, v5
	v_and_b32_e32 v6, 4, v6
	v_or3_b32 v5, v7, v5, v6
	v_mul_lo_u32 v5, v5, s11
	v_lshl_add_u32 v164, v4, 3, v5
	v_lshrrev_b32_e32 v4, 3, v0
	v_lshrrev_b32_e32 v0, 4, v0
	v_xor_b32_e32 v0, v0, v2
	s_addk_i32 s13, 0x200
	v_and_b32_e32 v3, 63, v2
	v_mul_lo_u32 v4, v4, s82
	v_lshlrev_b32_e32 v0, 3, v0
	s_and_b64 s[0:1], s[0:1], exec
	v_and_or_b32 v166, v0, 56, v4
	v_or_b32_e32 v0, s13, v3
	s_cselect_b32 s11, 0x44, 4
	s_lshl_b32 s13, s18, 8
	s_mul_i32 s14, s18, 0x78000
	s_add_i32 s0, s13, 0x2000
	s_lshl_b32 s12, s12, 10
	s_ashr_i32 s1, s0, 31
	s_add_i32 s14, s14, 0xf00000
	s_mul_hi_i32 s15, s0, 0x780
	s_add_u32 s14, s7, s14
	v_mov_b32_e32 v161, v1
	s_addc_u32 s15, s8, s15
	s_add_i32 s12, s12, 0
	v_lshlrev_b64 v[4:5], 1, v[160:161]
	v_lshl_add_u64 v[6:7], s[14:15], 0, v[4:5]
	s_mov_b32 m0, s12
	v_mov_b32_e32 v163, v1
	global_load_lds_dwordx4 v[6:7], off
	v_lshlrev_b64 v[6:7], 1, v[162:163]
	v_lshl_add_u64 v[8:9], s[14:15], 0, v[6:7]
	s_add_i32 m0, s12, 0x2000
	v_mov_b32_e32 v165, v1
	global_load_lds_dwordx4 v[8:9], off
	v_lshlrev_b64 v[8:9], 1, v[164:165]
	v_lshrrev_b32_e32 v3, 4, v0
	v_lshl_add_u64 v[10:11], s[14:15], 0, v[8:9]
	s_add_i32 m0, s12, 0x4000
	s_lshl_b64 s[14:15], s[0:1], 1
	v_xor_b32_e32 v3, v3, v2
	v_lshrrev_b32_e32 v0, 3, v0
	s_add_u32 s14, s9, s14
	v_mov_b32_e32 v167, v1
	v_lshlrev_b32_e32 v3, 3, v3
	v_mul_lo_u32 v0, v0, s82
	global_load_lds_dwordx4 v[10:11], off
	s_addc_u32 s15, s10, s15
	v_lshlrev_b64 v[10:11], 1, v[166:167]
	v_and_or_b32 v168, v3, 56, v0
	s_add_i32 m0, s12, 0x6000
	v_lshl_add_u64 v[12:13], s[14:15], 0, v[10:11]
	v_mov_b32_e32 v169, v1
	global_load_lds_dwordx4 v[12:13], off
	v_lshlrev_b64 v[12:13], 1, v[168:169]
	v_lshl_add_u64 v[14:15], s[14:15], 0, v[12:13]
	s_add_i32 s14, s13, 0x2040
	s_add_i32 m0, s12, 0x8000
	s_ashr_i32 s15, s14, 31
	s_mul_i32 s13, s14, 0x780
	global_load_lds_dwordx4 v[14:15], off
	s_mul_hi_i32 s1, s14, 0x780
	s_add_u32 s28, s7, s13
	s_waitcnt lgkmcnt(0)
	s_addc_u32 s29, s8, s1
	s_waitcnt vmcnt(0)
	s_barrier
; #define A2_SETKC(SOFF) _Pragma("unroll") for (int _i = 0; _i < NKB; ++_i) kc[_i] = kbase[_i] + (unsigned)(SOFF)
; #define A2_SETVC(SOFF) _Pragma("unroll") for (int _i = 0; _i < 4; ++_i) vc[_i] = vbase[_i] + (unsigned)(SOFF)
; template <int TYPE>
; __device__ __forceinline__ void attn_mfma_unit2(const AttnCtx& A, unsigned char* ws, LAS unsigned char* lds, int tid, const AUnit& u) {
;     ...
;         for (int ti = 0; ti < nt; ++ti) {
;             if (ti + 1 < nt) A2_DMA(ti + 1, snxt);
;             if (actP) { A2_SETVC(sprv); A2_FSM_PV(sA0, sA1, 0); }
;             actP = A2_ACTIVE(ti);
;             if (actP) { A2_SETKC(scur); A2_QK(sA0, sA1, ti, 0); A2_PSM(sA0, sA1); }
	s_add_i32 m0, s12, 0xa000
	v_lshl_add_u64 v[4:5], s[28:29], 0, v[4:5]
	global_load_lds_dwordx4 v[4:5], off
	v_lshl_add_u64 v[4:5], s[28:29], 0, v[6:7]
	s_add_i32 m0, s12, 0xc000
	s_lshl_b64 s[14:15], s[14:15], 1
	global_load_lds_dwordx4 v[4:5], off
	s_add_i32 m0, s12, 0xe000
	s_add_u32 s14, s9, s14
	v_lshl_add_u64 v[4:5], s[28:29], 0, v[8:9]
	s_addc_u32 s15, s10, s15
	global_load_lds_dwordx4 v[4:5], off
	s_add_i32 m0, s12, 0x10000
	v_lshl_add_u64 v[4:5], s[14:15], 0, v[10:11]
	global_load_lds_dwordx4 v[4:5], off
	v_lshl_add_u64 v[4:5], s[14:15], 0, v[12:13]
	s_add_i32 m0, s12, 0x12000
	v_lshrrev_b32_e32 v0, 1, v2
	global_load_lds_dwordx4 v[4:5], off
	v_bfe_u32 v2, v2, 1, 3
	v_bitop3_b32 v0, v17, v0, 7 bitop3:0x78
	v_bitop3_b32 v3, v17, v2, 2 bitop3:0x36
	v_bitop3_b32 v4, v17, v2, 4 bitop3:0x36
	v_bitop3_b32 v2, v17, v2, 6 bitop3:0x36
	v_lshl_add_u32 v66, v4, 4, 0
	s_movk_i32 s1, 0x180
	v_lshl_add_u32 v67, v2, 4, 0
	v_lshl_add_u32 v68, v3, 4, 0
	v_lshl_add_u32 v0, v0, 4, 0
	v_mad_u32_u24 v170, v16, s1, v66
	v_mad_u32_u24 v172, v16, s1, v67
	v_mad_u32_u24 v173, v16, s1, v68
	v_mad_u32_u24 v174, v16, s1, v0
	ds_read_b128 v[34:37], v170
	ds_read_b128 v[38:41], v170 offset:12288
	ds_read_b128 v[42:45], v172
	ds_read_b128 v[46:49], v172 offset:12288
	ds_read_b128 v[50:53], v173 offset:12288
	ds_read_b128 v[54:57], v173
	ds_read_b128 v[58:61], v174 offset:12288
	ds_read_b128 v[62:65], v174
	s_mov_b32 s29, 1
	v_lshlrev_b32_e32 v69, 7, v16
	s_mov_b32 s1, 0xa000
	v_readlane_b32 s64, v254, 25
	v_readlane_b32 s65, v254, 26
	v_readlane_b32 s66, v254, 27
	v_readlane_b32 s67, v254, 28
	v_readlane_b32 s68, v254, 29
	v_readlane_b32 s69, v254, 30
	v_readlane_b32 s70, v254, 31
	v_readlane_b32 s71, v254, 32
	v_readlane_b32 s72, v254, 33
	v_readlane_b32 s73, v254, 34
	v_readlane_b32 s74, v254, 35
	v_readlane_b32 s75, v254, 36
	v_readlane_b32 s76, v254, 37
	v_readlane_b32 s77, v254, 38
	v_readlane_b32 s78, v254, 39
	v_readlane_b32 s79, v254, 40
	s_mov_b32 s65, s64
	s_mov_b32 s66, s64
	s_mov_b32 s67, s64
	s_mov_b32 s68, s64
	s_mov_b32 s69, s64
	s_mov_b32 s70, s64
	s_mov_b32 s71, s64
	s_mov_b32 s72, s64
	s_mov_b32 s73, s64
	s_mov_b32 s74, s64
	s_mov_b32 s75, s64
	s_mov_b32 s76, s64
	s_mov_b32 s77, s64
	s_mov_b32 s78, s64
	s_mov_b32 s79, s64
	v_mov_b64_e32 v[2:3], s[64:65]
	s_mov_b32 s36, s64
	v_mov_b64_e32 v[4:5], s[66:67]
	v_mov_b64_e32 v[6:7], s[68:69]
	v_mov_b64_e32 v[8:9], s[70:71]
	v_mov_b64_e32 v[10:11], s[72:73]
	v_mov_b64_e32 v[12:13], s[74:75]
	v_mov_b64_e32 v[14:15], s[76:77]
	v_mov_b64_e32 v[16:17], s[78:79]
	v_writelane_b32 v254, s36, 25
	s_waitcnt lgkmcnt(0)
	v_mfma_f32_32x32x16_bf16 v[18:33], v[62:65], v[112:115], v[2:17]
	v_writelane_b32 v254, s37, 26
	v_writelane_b32 v254, s38, 27
	v_writelane_b32 v254, s39, 28
	v_writelane_b32 v254, s40, 29
	v_writelane_b32 v254, s41, 30
	v_writelane_b32 v254, s42, 31
	v_writelane_b32 v254, s43, 32
	v_mfma_f32_32x32x16_bf16 v[2:17], v[58:61], v[112:115], v[2:17]
	v_writelane_b32 v254, s44, 33
	v_writelane_b32 v254, s45, 34
	v_writelane_b32 v254, s46, 35
	v_writelane_b32 v254, s47, 36
	v_writelane_b32 v254, s48, 37
	v_writelane_b32 v254, s49, 38
	v_writelane_b32 v254, s50, 39
	v_mfma_f32_32x32x16_bf16 v[18:33], v[54:57], v[116:119], v[18:33]
	v_writelane_b32 v254, s51, 40
	v_mfma_f32_32x32x16_bf16 v[2:17], v[50:53], v[116:119], v[2:17]
	ds_read_b128 v[50:53], v173 offset:12416
	ds_read_b128 v[54:57], v173 offset:128
	ds_read_b128 v[58:61], v174 offset:12416
	ds_read_b128 v[62:65], v174 offset:128
	v_mfma_f32_32x32x16_bf16 v[18:33], v[34:37], v[120:123], v[18:33]
	v_mfma_f32_32x32x16_bf16 v[2:17], v[38:41], v[120:123], v[2:17]
	v_mfma_f32_32x32x16_bf16 v[18:33], v[42:45], v[124:127], v[18:33]
	v_mfma_f32_32x32x16_bf16 v[2:17], v[46:49], v[124:127], v[2:17]
	ds_read_b128 v[34:37], v170 offset:128
	ds_read_b128 v[38:41], v170 offset:12416
	ds_read_b128 v[42:45], v172 offset:128
	ds_read_b128 v[46:49], v172 offset:12416
	s_waitcnt lgkmcnt(0)
	v_mfma_f32_32x32x16_bf16 v[18:33], v[62:65], v[128:131], v[18:33]
	v_mfma_f32_32x32x16_bf16 v[2:17], v[58:61], v[128:131], v[2:17]
	v_mfma_f32_32x32x16_bf16 v[18:33], v[54:57], v[132:135], v[18:33]
	v_mfma_f32_32x32x16_bf16 v[2:17], v[50:53], v[132:135], v[2:17]
	ds_read_b128 v[50:53], v173 offset:12544
	ds_read_b128 v[54:57], v173 offset:256
	ds_read_b128 v[58:61], v174 offset:12544
	ds_read_b128 v[62:65], v174 offset:256
	v_mfma_f32_32x32x16_bf16 v[18:33], v[34:37], v[136:139], v[18:33]
	v_mfma_f32_32x32x16_bf16 v[2:17], v[38:41], v[136:139], v[2:17]
	v_mfma_f32_32x32x16_bf16 v[18:33], v[42:45], v[140:143], v[18:33]
	v_mfma_f32_32x32x16_bf16 v[2:17], v[46:49], v[140:143], v[2:17]
	ds_read_b128 v[34:37], v170 offset:256
	ds_read_b128 v[38:41], v170 offset:12544
	ds_read_b128 v[42:45], v172 offset:256
	ds_read_b128 v[46:49], v172 offset:12544
	s_waitcnt lgkmcnt(0)
	v_mfma_f32_32x32x16_bf16 v[18:33], v[62:65], v[144:147], v[18:33]
	v_mfma_f32_32x32x16_bf16 v[2:17], v[58:61], v[144:147], v[2:17]
	v_mfma_f32_32x32x16_bf16 v[18:33], v[54:57], v[148:151], v[18:33]
	v_mfma_f32_32x32x16_bf16 v[2:17], v[50:53], v[148:151], v[2:17]
	v_mfma_f32_32x32x16_bf16 v[18:33], v[34:37], v[152:155], v[18:33]
	v_mfma_f32_32x32x16_bf16 v[18:33], v[42:45], v[156:159], v[18:33]
	v_mfma_f32_32x32x16_bf16 v[2:17], v[38:41], v[152:155], v[2:17]
	s_nop 10
	v_max_f32_e32 v34, v19, v19
	v_max_f32_e32 v35, v18, v18
	v_max_f32_e32 v34, v35, v34
	v_max3_f32 v34, v34, v20, v21
	v_max3_f32 v34, v34, v22, v23
	v_max3_f32 v34, v34, v24, v25
	v_max3_f32 v34, v34, v26, v27
	v_mfma_f32_32x32x16_bf16 v[2:17], v[46:49], v[156:159], v[2:17]
	v_max3_f32 v34, v34, v28, v29
	v_max3_f32 v34, v34, v30, v31
	v_max3_f32 v34, v34, v32, v33
	s_waitcnt vmcnt(0)
	s_barrier
; #define A2_WAITN(n) asm volatile("s_waitcnt vmcnt(%0)" :: "n"(n) : "memory")
; #define A2_BAR() do { __builtin_amdgcn_s_barrier(); asm volatile("" ::: "memory"); } while (0)
; #define A2_SETKC(SOFF) _Pragma("unroll") for (int _i = 0; _i < NKB; ++_i) kc[_i] = kbase[_i] + (unsigned)(SOFF)
; #define A2_SETVC(SOFF) _Pragma("unroll") for (int _i = 0; _i < 4; ++_i) vc[_i] = vbase[_i] + (unsigned)(SOFF)
; template <int TYPE>
; __device__ __forceinline__ void attn_mfma_unit2(const AttnCtx& A, unsigned char* ws, LAS unsigned char* lds, int tid, const AUnit& u) {
;     ...
;         for (int ti = 0; ti < nt; ++ti) {
;             if (ti + 1 < nt) A2_DMA(ti + 1, snxt);
;             if (actP) { A2_SETVC(sprv); A2_FSM_PV(sA0, sA1, 0); }
;             actP = A2_ACTIVE(ti);
;             if (actP) { A2_SETKC(scur); A2_QK(sA0, sA1, ti, 0); A2_PSM(sA0, sA1); }
;             A2_WAITN(0); A2_BAR();
;             sprv = scur; scur = snxt; snxt = snxt == 2 * STG ? 0 : snxt + STG;
	v_add_u32_e32 v183, v0, v69
	s_nop 6
	v_max3_f32 v34, v34, v2, v3
	v_max3_f32 v34, v34, v4, v5
	v_max3_f32 v34, v34, v6, v7
	v_max3_f32 v34, v34, v8, v9
	v_max3_f32 v34, v34, v10, v11
	v_max3_f32 v34, v34, v12, v13
	v_max3_f32 v34, v34, v14, v15
	v_max3_f32 v34, v34, v16, v17
	v_mov_b32_e32 v35, v34
	s_nop 1
	v_permlane32_swap_b32_e32 v34, v35
	v_max_f32_e32 v35, v35, v35
	v_max_f32_e32 v34, v34, v34
	v_max_f32_e32 v34, v34, v35
	v_sub_f32_e32 v93, v15, v34
	v_sub_f32_e32 v92, v14, v34
	v_mov_b32_e32 v14, v1
	v_mov_b32_e32 v15, v1
	v_add_f32_e32 v181, 0, v34
	v_sub_f32_e32 v111, v33, v34
	v_sub_f32_e32 v110, v32, v34
	v_sub_f32_e32 v109, v31, v34
	v_sub_f32_e32 v108, v30, v34
	v_sub_f32_e32 v107, v29, v34
	v_sub_f32_e32 v106, v28, v34
	v_sub_f32_e32 v105, v27, v34
	v_sub_f32_e32 v104, v26, v34
	v_sub_f32_e32 v103, v25, v34
	v_sub_f32_e32 v102, v24, v34
	v_sub_f32_e32 v101, v23, v34
	v_sub_f32_e32 v100, v22, v34
	v_sub_f32_e32 v99, v21, v34
	v_sub_f32_e32 v98, v20, v34
	v_sub_f32_e32 v97, v19, v34
	v_sub_f32_e32 v96, v18, v34
	v_sub_f32_e32 v95, v17, v34
	v_sub_f32_e32 v94, v16, v34
	v_sub_f32_e32 v91, v13, v34
	v_sub_f32_e32 v90, v12, v34
	v_sub_f32_e32 v89, v11, v34
	v_sub_f32_e32 v88, v10, v34
	v_sub_f32_e32 v87, v9, v34
	v_sub_f32_e32 v86, v8, v34
	v_sub_f32_e32 v85, v7, v34
	v_sub_f32_e32 v84, v6, v34
	v_sub_f32_e32 v83, v5, v34
	v_sub_f32_e32 v82, v4, v34
	v_sub_f32_e32 v81, v3, v34
	v_sub_f32_e32 v80, v2, v34
	v_add_u32_e32 v182, v68, v69
	v_add_u32_e32 v180, v66, v69
	v_add_u32_e32 v175, v67, v69
	s_lshl_b32 s13, s18, 12
	v_mov_b32_e32 v0, v1
	v_mov_b32_e32 v2, v1
	v_mov_b32_e32 v3, v1
	v_mov_b32_e32 v4, v1
	v_mov_b32_e32 v5, v1
	v_mov_b32_e32 v6, v1
	v_mov_b32_e32 v7, v1
	v_mov_b32_e32 v8, v1
	v_mov_b32_e32 v9, v1
	v_mov_b32_e32 v10, v1
	v_mov_b32_e32 v11, v1
	v_mov_b32_e32 v12, v1
	v_mov_b32_e32 v13, v1
	v_mov_b64_e32 v[30:31], v[14:15]
	v_mov_b64_e32 v[46:47], v[14:15]
	v_mov_b64_e32 v[62:63], v[14:15]
	v_mov_b64_e32 v[78:79], v[14:15]
	s_mov_b32 s28, 0
	s_addk_i32 s13, 0xff40
	s_mov_b32 s36, 0x14000
	v_mov_b32_e32 v171, 0
	v_mov_b64_e32 v[28:29], v[12:13]
	v_mov_b64_e32 v[26:27], v[10:11]
	v_mov_b64_e32 v[24:25], v[8:9]
	v_mov_b64_e32 v[22:23], v[6:7]
	v_mov_b64_e32 v[20:21], v[4:5]
	v_mov_b64_e32 v[18:19], v[2:3]
	v_mov_b64_e32 v[16:17], v[0:1]
	v_mov_b64_e32 v[44:45], v[12:13]
	v_mov_b64_e32 v[42:43], v[10:11]
	v_mov_b64_e32 v[40:41], v[8:9]
	v_mov_b64_e32 v[38:39], v[6:7]
	v_mov_b64_e32 v[36:37], v[4:5]
	v_mov_b64_e32 v[34:35], v[2:3]
	v_mov_b64_e32 v[32:33], v[0:1]
	v_mov_b64_e32 v[60:61], v[12:13]
	v_mov_b64_e32 v[58:59], v[10:11]
	v_mov_b64_e32 v[56:57], v[8:9]
	v_mov_b64_e32 v[54:55], v[6:7]
	v_mov_b64_e32 v[52:53], v[4:5]
	v_mov_b64_e32 v[50:51], v[2:3]
	v_mov_b64_e32 v[48:49], v[0:1]
	v_mov_b64_e32 v[76:77], v[12:13]
	v_mov_b64_e32 v[74:75], v[10:11]
	v_mov_b64_e32 v[72:73], v[8:9]
	v_mov_b64_e32 v[70:71], v[6:7]
	v_mov_b64_e32 v[68:69], v[4:5]
	v_mov_b64_e32 v[66:67], v[2:3]
	v_mov_b64_e32 v[64:65], v[0:1]
	s_add_i32 s15, s29, 1
	s_mov_b32 s14, s36
	v_add_u32_e32 v0, s28, v183
	ds_read_b128 v[2:5], v0 offset:24576
	ds_read_b128 v[6:9], v0 offset:28672
	ds_read_b128 v[10:13], v0 offset:32768
	ds_read_b128 v[184:187], v0 offset:36864
	s_branch .LBB0_2904

.LBB0_2904:
	v_exp_f32_e32 v14, v96
	v_exp_f32_e32 v190, v97
	v_exp_f32_e32 v98, v98
	v_exp_f32_e32 v192, v99
	v_exp_f32_e32 v15, v100
	v_exp_f32_e32 v191, v101
	v_exp_f32_e32 v99, v102
	v_exp_f32_e32 v193, v103
	v_add_u32_e32 v0, s28, v182
	v_pk_add_f32 v[96:97], v[14:15], v[190:191]
	v_pk_add_f32 v[100:101], v[98:99], v[192:193]
	s_nop 0
	v_pk_add_f32 v[96:97], v[96:97], v[100:101]
	v_cvt_pk_bf16_f32 v99, v99, v193
	v_pk_add_f32 v[202:203], v[96:97], v[96:97] op_sel_hi:[0,1]
	v_cvt_pk_bf16_f32 v96, v14, v190
	v_cvt_pk_bf16_f32 v97, v98, v192
	v_cvt_pk_bf16_f32 v98, v15, v191
	ds_read_b128 v[100:103], v0 offset:24576
	ds_read_b128 v[190:193], v0 offset:28672
	ds_read_b128 v[194:197], v0 offset:32768
	ds_read_b128 v[198:201], v0 offset:36864
	s_waitcnt lgkmcnt(0)
	v_mfma_f32_32x32x16_bf16 v[64:79], v[2:5], v[96:99], v[64:79]
	v_mfma_f32_32x32x16_bf16 v[48:63], v[6:9], v[96:99], v[48:63]
	v_mfma_f32_32x32x16_bf16 v[32:47], v[10:13], v[96:99], v[32:47]
	v_mfma_f32_32x32x16_bf16 v[16:31], v[184:187], v[96:99], v[16:31]
	s_cmp_ge_u32 s15, s11
	s_cbranch_scc1 .Lmla_dma_skip
	s_cmp_lt_u32 s29, 3
	s_cselect_b32 s29, s15, s29
	s_cselect_b32 s36, s0, s13
	s_lshl_b32 s29, s29, 6
	s_add_i32 s36, s29, s36
	s_ashr_i32 s37, s36, 31
	s_mul_i32 s38, s36, 0x780
	s_mul_hi_i32 s29, s36, 0x780
	s_add_u32 s38, s7, s38
	s_addc_u32 s39, s8, s29
	s_add_i32 s29, s12, s14
	v_lshl_add_u64 v[2:3], v[160:161], 1, s[38:39]
	s_mov_b32 m0, s29
	s_lshl_b64 s[36:37], s[36:37], 1
	global_load_lds_dwordx4 v[2:3], off
	v_lshl_add_u64 v[2:3], v[162:163], 1, s[38:39]
	s_add_i32 m0, s29, 0x2000
	s_nop 0
	global_load_lds_dwordx4 v[2:3], off
	s_add_i32 m0, s29, 0x4000
	s_add_u32 s36, s9, s36
	v_lshl_add_u64 v[2:3], v[164:165], 1, s[38:39]
	s_addc_u32 s37, s10, s37
	global_load_lds_dwordx4 v[2:3], off
	s_add_i32 m0, s29, 0x6000
	v_lshl_add_u64 v[2:3], v[166:167], 1, s[36:37]
	global_load_lds_dwordx4 v[2:3], off
	v_lshl_add_u64 v[2:3], v[168:169], 1, s[36:37]
	s_add_i32 m0, s29, 0x8000
	s_nop 0
	global_load_lds_dwordx4 v[2:3], off
.Lmla_dma_skip:
	v_exp_f32_e32 v2, v104
	v_exp_f32_e32 v4, v105
	v_exp_f32_e32 v3, v106
	v_exp_f32_e32 v5, v107
	v_exp_f32_e32 v6, v108
	v_exp_f32_e32 v8, v109
	v_exp_f32_e32 v7, v110
	v_exp_f32_e32 v9, v111
	v_pk_add_f32 v[10:11], v[2:3], v[4:5]
	v_add_u32_e32 v0, s28, v180
	v_pk_add_f32 v[14:15], v[10:11], v[10:11] op_sel_hi:[0,1]
	v_pk_add_f32 v[10:11], v[6:7], v[8:9]
	v_cvt_pk_bf16_f32 v2, v2, v4
	v_pk_add_f32 v[184:185], v[10:11], v[10:11] op_sel_hi:[0,1]
	v_cvt_pk_bf16_f32 v3, v3, v5
	v_cvt_pk_bf16_f32 v4, v6, v8
	v_cvt_pk_bf16_f32 v5, v7, v9
	ds_read_b128 v[6:9], v0 offset:24576
	ds_read_b128 v[10:13], v0 offset:28672
	ds_read_b128 v[96:99], v0 offset:32768
	ds_read_b128 v[104:107], v0 offset:36864
	v_mfma_f32_32x32x16_bf16 v[64:79], v[100:103], v[2:5], v[64:79]
	v_mfma_f32_32x32x16_bf16 v[48:63], v[190:193], v[2:5], v[48:63]
	v_mfma_f32_32x32x16_bf16 v[32:47], v[194:197], v[2:5], v[32:47]
	v_mfma_f32_32x32x16_bf16 v[16:31], v[198:201], v[2:5], v[16:31]
	v_exp_f32_e32 v0, v80
	v_exp_f32_e32 v2, v81
	v_exp_f32_e32 v3, v82
	v_exp_f32_e32 v4, v83
	v_exp_f32_e32 v5, v84
	v_exp_f32_e32 v14, v85
	v_exp_f32_e32 v80, v86
	v_exp_f32_e32 v81, v87
	v_add_f32_e32 v187, v0, v2
	v_cvt_pk_bf16_f32 v2, v0, v2
	v_add_u32_e32 v0, s28, v175
	v_add_f32_e32 v191, v3, v4
	v_add_f32_e32 v193, v5, v14
	v_add_f32_e32 v195, v80, v81
	v_cvt_pk_bf16_f32 v3, v3, v4
	v_cvt_pk_bf16_f32 v4, v5, v14
	v_cvt_pk_bf16_f32 v5, v80, v81
	ds_read_b128 v[80:83], v0 offset:24576
	ds_read_b128 v[84:87], v0 offset:28672
	ds_read_b128 v[100:103], v0 offset:32768
	ds_read_b128 v[108:111], v0 offset:36864
	s_waitcnt lgkmcnt(0)
	v_mfma_f32_32x32x16_bf16 v[64:79], v[6:9], v[2:5], v[64:79]
	v_mfma_f32_32x32x16_bf16 v[48:63], v[10:13], v[2:5], v[48:63]
	v_mfma_f32_32x32x16_bf16 v[32:47], v[96:99], v[2:5], v[32:47]
	v_mfma_f32_32x32x16_bf16 v[16:31], v[104:107], v[2:5], v[16:31]
	v_exp_f32_e32 v186, v88
	v_exp_f32_e32 v190, v89
	v_exp_f32_e32 v192, v90
	v_exp_f32_e32 v194, v91
	v_exp_f32_e32 v14, v92
	v_exp_f32_e32 v184, v93
	v_exp_f32_e32 v202, v94
	v_exp_f32_e32 v0, v95
	v_cvt_pk_bf16_f32 v2, v186, v190
	v_cvt_pk_bf16_f32 v3, v192, v194
	v_cvt_pk_bf16_f32 v4, v14, v184
	v_cvt_pk_bf16_f32 v5, v202, v0
	s_nop 1
	v_mfma_f32_32x32x16_bf16 v[64:79], v[80:83], v[2:5], v[64:79]
	v_add_f32_e64 v6, v186, v190
	v_add_f32_e64 v7, v187, v191
	v_add_f32_e64 v8, v192, v194
	v_add_f32_e64 v9, v193, v195
	v_add_f32_e64 v10, v202, v0
	v_add_f32_e64 v11, v203, v1
	v_pk_add_f32 v[6:7], v[6:7], v[8:9]
	v_pk_add_f32 v[8:9], v[14:15], v[184:185]
	s_nop 0
	v_pk_add_f32 v[8:9], v[8:9], v[10:11]
	v_mfma_f32_32x32x16_bf16 v[48:63], v[84:87], v[2:5], v[48:63]
	v_add_f32_e64 v6, v6, v8
	v_add_f32_e64 v7, v7, v9
	v_pk_add_f32 v[6:7], v[6:7], v[6:7] op_sel:[0,1] op_sel_hi:[1,0]
	v_mfma_f32_32x32x16_bf16 v[32:47], v[100:103], v[2:5], v[32:47]
	v_mfma_f32_32x32x16_bf16 v[16:31], v[108:111], v[2:5], v[16:31]
	v_mov_b32_e32 v0, v6
	s_nop 1
	v_permlane32_swap_b32_e32 v6, v0
	v_add_f32_e32 v0, v6, v0
	v_add_f32_e32 v171, v171, v0
	v_add_u32_e32 v0, s1, v174
	v_add_u32_e32 v14, s1, v173
	v_add_u32_e32 v15, s1, v170
	ds_read_b128 v[2:5], v0
	ds_read_b128 v[6:9], v0 offset:12288
	ds_read_b128 v[10:13], v14
	ds_read_b128 v[184:187], v14 offset:12288
	v_add_u32_e32 v206, s1, v172
	ds_read_b128 v[190:193], v15
	ds_read_b128 v[194:197], v15 offset:12288
	ds_read_b128 v[198:201], v206
	ds_read_b128 v[202:205], v206 offset:12288
	v_xor_b32_e32 v80, 0x80000000, v181
	v_mov_b32_e32 v81, v80
	v_mov_b32_e32 v82, v80
	v_mov_b32_e32 v83, v80
	v_mov_b32_e32 v84, v80
	v_mov_b32_e32 v85, v80
	v_mov_b32_e32 v86, v80
	v_mov_b32_e32 v87, v80
	v_mov_b32_e32 v88, v80
	v_mov_b32_e32 v89, v80
	v_mov_b32_e32 v90, v80
	v_mov_b32_e32 v91, v80
	v_mov_b32_e32 v92, v80
	v_mov_b32_e32 v93, v80
	v_mov_b32_e32 v94, v80
	v_mov_b32_e32 v95, v80
	s_waitcnt lgkmcnt(0)
	s_nop 0
	v_mfma_f32_32x32x16_bf16 v[96:111], v[2:5], v[112:115], v[80:95]
	v_mfma_f32_32x32x16_bf16 v[80:95], v[6:9], v[112:115], v[80:95]
	v_mfma_f32_32x32x16_bf16 v[96:111], v[10:13], v[116:119], v[96:111]
	v_mfma_f32_32x32x16_bf16 v[80:95], v[184:187], v[116:119], v[80:95]
	ds_read_b128 v[2:5], v14 offset:12416
	ds_read_b128 v[6:9], v14 offset:128
	ds_read_b128 v[10:13], v0 offset:12416
	ds_read_b128 v[184:187], v0 offset:128
	v_mfma_f32_32x32x16_bf16 v[96:111], v[190:193], v[120:123], v[96:111]
	v_mfma_f32_32x32x16_bf16 v[80:95], v[194:197], v[120:123], v[80:95]
	v_mfma_f32_32x32x16_bf16 v[96:111], v[198:201], v[124:127], v[96:111]
	v_mfma_f32_32x32x16_bf16 v[80:95], v[202:205], v[124:127], v[80:95]
	ds_read_b128 v[190:193], v15 offset:128
	ds_read_b128 v[194:197], v15 offset:12416
	ds_read_b128 v[198:201], v206 offset:128
	ds_read_b128 v[202:205], v206 offset:12416
	s_waitcnt lgkmcnt(0)
	v_mfma_f32_32x32x16_bf16 v[96:111], v[184:187], v[128:131], v[96:111]
	v_mfma_f32_32x32x16_bf16 v[80:95], v[10:13], v[128:131], v[80:95]
	v_mfma_f32_32x32x16_bf16 v[96:111], v[6:9], v[132:135], v[96:111]
	v_mfma_f32_32x32x16_bf16 v[80:95], v[2:5], v[132:135], v[80:95]
	ds_read_b128 v[2:5], v14 offset:12544
	ds_read_b128 v[6:9], v14 offset:256
	ds_read_b128 v[10:13], v0 offset:12544
	ds_read_b128 v[184:187], v0 offset:256
	v_mfma_f32_32x32x16_bf16 v[96:111], v[190:193], v[136:139], v[96:111]
	v_mfma_f32_32x32x16_bf16 v[80:95], v[194:197], v[136:139], v[80:95]
	v_mfma_f32_32x32x16_bf16 v[96:111], v[198:201], v[140:143], v[96:111]
	v_mfma_f32_32x32x16_bf16 v[80:95], v[202:205], v[140:143], v[80:95]
	ds_read_b128 v[190:193], v15 offset:256
	ds_read_b128 v[194:197], v15 offset:12544
	ds_read_b128 v[198:201], v206 offset:256
	ds_read_b128 v[202:205], v206 offset:12544
	s_waitcnt lgkmcnt(0)
	v_mfma_f32_32x32x16_bf16 v[96:111], v[184:187], v[144:147], v[96:111]
	v_mfma_f32_32x32x16_bf16 v[80:95], v[10:13], v[144:147], v[80:95]
	v_mfma_f32_32x32x16_bf16 v[96:111], v[6:9], v[148:151], v[96:111]
	v_mfma_f32_32x32x16_bf16 v[80:95], v[2:5], v[148:151], v[80:95]
	v_mfma_f32_32x32x16_bf16 v[96:111], v[190:193], v[152:155], v[96:111]
	v_mfma_f32_32x32x16_bf16 v[96:111], v[198:201], v[156:159], v[96:111]
	v_mfma_f32_32x32x16_bf16 v[80:95], v[194:197], v[152:155], v[80:95]
	s_nop 10
	v_max_f32_e32 v0, v97, v97
	v_max_f32_e32 v2, v96, v96
	v_max_f32_e32 v0, v2, v0
	v_max3_f32 v0, v0, v98, v99
	v_max3_f32 v0, v0, v100, v101
	v_max3_f32 v0, v0, v102, v103
	v_max3_f32 v0, v0, v104, v105
	v_mfma_f32_32x32x16_bf16 v[80:95], v[202:205], v[156:159], v[80:95]
	v_max3_f32 v0, v0, v106, v107
	v_max3_f32 v0, v0, v108, v109
	v_max3_f32 v0, v0, v110, v111
	s_mov_b32 s28, 0x41000000
	s_nop 7
	v_max3_f32 v0, v0, v80, v81
	v_max3_f32 v0, v0, v82, v83
	v_max3_f32 v0, v0, v84, v85
	v_max3_f32 v0, v0, v86, v87
	v_max3_f32 v0, v0, v88, v89
	v_max3_f32 v0, v0, v90, v91
	v_max3_f32 v0, v0, v92, v93
	v_max3_f32 v0, v0, v94, v95
	v_mov_b32_e32 v2, v0
	s_nop 1
	v_permlane32_swap_b32_e32 v0, v2
	v_max_f32_e32 v2, v2, v2
	v_max_f32_e32 v0, v0, v0
	v_max_f32_e32 v0, v0, v2
	v_cmp_ge_f32_e32 vcc, s28, v0
	s_cmp_eq_u64 vcc, exec
	s_cbranch_scc1 .LBB0_2906
	v_max_f32_e32 v0, v0, v0
	v_max_f32_e32 v2, 0, v0
	v_exp_f32_e64 v0, -v2
	v_add_f32_e32 v181, v181, v2
	v_sub_f32_e32 v111, v111, v2
	v_sub_f32_e32 v110, v110, v2
	v_pk_mul_f32 v[78:79], v[78:79], v[0:1] op_sel_hi:[1,0]
	v_pk_mul_f32 v[76:77], v[76:77], v[0:1] op_sel_hi:[1,0]
	v_pk_mul_f32 v[74:75], v[74:75], v[0:1] op_sel_hi:[1,0]
	v_pk_mul_f32 v[72:73], v[72:73], v[0:1] op_sel_hi:[1,0]
	v_pk_mul_f32 v[70:71], v[70:71], v[0:1] op_sel_hi:[1,0]
	v_pk_mul_f32 v[68:69], v[68:69], v[0:1] op_sel_hi:[1,0]
	v_pk_mul_f32 v[66:67], v[66:67], v[0:1] op_sel_hi:[1,0]
	v_pk_mul_f32 v[64:65], v[64:65], v[0:1] op_sel_hi:[1,0]
	v_pk_mul_f32 v[62:63], v[62:63], v[0:1] op_sel_hi:[1,0]
	v_pk_mul_f32 v[60:61], v[60:61], v[0:1] op_sel_hi:[1,0]
	v_pk_mul_f32 v[58:59], v[58:59], v[0:1] op_sel_hi:[1,0]
	v_pk_mul_f32 v[56:57], v[56:57], v[0:1] op_sel_hi:[1,0]
	v_pk_mul_f32 v[54:55], v[54:55], v[0:1] op_sel_hi:[1,0]
	v_pk_mul_f32 v[52:53], v[52:53], v[0:1] op_sel_hi:[1,0]
	v_pk_mul_f32 v[50:51], v[50:51], v[0:1] op_sel_hi:[1,0]
	v_pk_mul_f32 v[48:49], v[48:49], v[0:1] op_sel_hi:[1,0]
	v_pk_mul_f32 v[46:47], v[46:47], v[0:1] op_sel_hi:[1,0]
	v_pk_mul_f32 v[44:45], v[44:45], v[0:1] op_sel_hi:[1,0]
	v_pk_mul_f32 v[42:43], v[42:43], v[0:1] op_sel_hi:[1,0]
	v_pk_mul_f32 v[40:41], v[40:41], v[0:1] op_sel_hi:[1,0]
	v_pk_mul_f32 v[38:39], v[38:39], v[0:1] op_sel_hi:[1,0]
	v_pk_mul_f32 v[36:37], v[36:37], v[0:1] op_sel_hi:[1,0]
	v_pk_mul_f32 v[34:35], v[34:35], v[0:1] op_sel_hi:[1,0]
	v_pk_mul_f32 v[32:33], v[32:33], v[0:1] op_sel_hi:[1,0]
	v_pk_mul_f32 v[30:31], v[30:31], v[0:1] op_sel_hi:[1,0]
	v_pk_mul_f32 v[28:29], v[28:29], v[0:1] op_sel_hi:[1,0]
	v_pk_mul_f32 v[26:27], v[26:27], v[0:1] op_sel_hi:[1,0]
	v_pk_mul_f32 v[24:25], v[24:25], v[0:1] op_sel_hi:[1,0]
	v_pk_mul_f32 v[22:23], v[22:23], v[0:1] op_sel_hi:[1,0]
	v_pk_mul_f32 v[20:21], v[20:21], v[0:1] op_sel_hi:[1,0]
	v_pk_mul_f32 v[18:19], v[18:19], v[0:1] op_sel_hi:[1,0]
	v_pk_mul_f32 v[16:17], v[16:17], v[0:1] op_sel_hi:[1,0]
	v_sub_f32_e32 v109, v109, v2
	v_sub_f32_e32 v108, v108, v2
	v_sub_f32_e32 v107, v107, v2
	v_sub_f32_e32 v106, v106, v2
	v_sub_f32_e32 v105, v105, v2
	v_sub_f32_e32 v104, v104, v2
	v_sub_f32_e32 v103, v103, v2
	v_sub_f32_e32 v102, v102, v2
	v_sub_f32_e32 v101, v101, v2
	v_sub_f32_e32 v100, v100, v2
	v_sub_f32_e32 v99, v99, v2
	v_sub_f32_e32 v98, v98, v2
	v_sub_f32_e32 v97, v97, v2
	v_sub_f32_e32 v96, v96, v2
	v_sub_f32_e32 v95, v95, v2
	v_sub_f32_e32 v94, v94, v2
	v_sub_f32_e32 v93, v93, v2
	v_sub_f32_e32 v92, v92, v2
	v_sub_f32_e32 v91, v91, v2
	v_sub_f32_e32 v90, v90, v2
	v_sub_f32_e32 v89, v89, v2
	v_sub_f32_e32 v88, v88, v2
	v_sub_f32_e32 v87, v87, v2
	v_sub_f32_e32 v86, v86, v2
	v_sub_f32_e32 v85, v85, v2
	v_sub_f32_e32 v84, v84, v2
	v_sub_f32_e32 v83, v83, v2
	v_sub_f32_e32 v82, v82, v2
	v_sub_f32_e32 v81, v81, v2
	v_sub_f32_e32 v80, v80, v2
	v_mul_f32_e32 v171, v171, v0
; #define A2_WAITN(n) asm volatile("s_waitcnt vmcnt(%0)" :: "n"(n) : "memory")
; #define A2_BAR() do { __builtin_amdgcn_s_barrier(); asm volatile("" ::: "memory"); } while (0)
; #define A2_SETVC(SOFF) _Pragma("unroll") for (int _i = 0; _i < 4; ++_i) vc[_i] = vbase[_i] + (unsigned)(SOFF)
; template <int TYPE>
; __device__ __forceinline__ void attn_mfma_unit2(const AttnCtx& A, unsigned char* ws, LAS unsigned char* lds, int tid, const AUnit& u) {
;     ...
;             A2_WAITN(0); A2_BAR();
;             sprv = scur; scur = snxt; snxt = snxt == 2 * STG ? 0 : snxt + STG;
;         }
;         if (actP) { A2_SETVC(sprv); A2_FSM_PV(sA0, sA1, 0); }
.LBB0_2906:
	v_add_u32_e32 v0, s1, v183
	ds_read_b128 v[2:5], v0 offset:24576
	ds_read_b128 v[6:9], v0 offset:28672
	ds_read_b128 v[10:13], v0 offset:32768
	ds_read_b128 v[184:187], v0 offset:36864
	s_waitcnt vmcnt(0)
	s_barrier
	s_add_i32 s28, s14, 0xa000
	s_cmp_lg_u32 s14, 0x14000
	s_cselect_b32 s36, s28, 0
	s_cmp_lg_u32 s11, s15
	s_cbranch_scc1 .LBB0_2902
	s_waitcnt lgkmcnt(0)
	v_add_u32_e32 v0, s1, v183
	ds_read_b128 v[2:5], v0 offset:24576
	ds_read_b128 v[6:9], v0 offset:28672
	ds_read_b128 v[10:13], v0 offset:32768
	ds_read_b128 v[112:115], v0 offset:36864
	v_exp_f32_e32 v14, v96
	v_exp_f32_e32 v116, v97
	v_exp_f32_e32 v98, v98
	v_exp_f32_e32 v118, v99
	v_exp_f32_e32 v15, v100
	v_exp_f32_e32 v117, v101
	v_exp_f32_e32 v99, v102
	v_exp_f32_e32 v119, v103
	v_add_u32_e32 v0, s1, v182
	v_pk_add_f32 v[96:97], v[14:15], v[116:117]
	v_pk_add_f32 v[100:101], v[98:99], v[118:119]
	s_nop 0
	v_pk_add_f32 v[96:97], v[96:97], v[100:101]
	v_cvt_pk_bf16_f32 v99, v99, v119
	v_pk_add_f32 v[128:129], v[96:97], v[96:97] op_sel_hi:[0,1]
	v_cvt_pk_bf16_f32 v96, v14, v116
	v_cvt_pk_bf16_f32 v97, v98, v118
	v_cvt_pk_bf16_f32 v98, v15, v117
	ds_read_b128 v[100:103], v0 offset:24576
	ds_read_b128 v[116:119], v0 offset:28672
	ds_read_b128 v[120:123], v0 offset:32768
	ds_read_b128 v[124:127], v0 offset:36864
	s_waitcnt lgkmcnt(0)
	v_mfma_f32_32x32x16_bf16 v[64:79], v[2:5], v[96:99], v[64:79]
	v_mfma_f32_32x32x16_bf16 v[48:63], v[6:9], v[96:99], v[48:63]
	v_mfma_f32_32x32x16_bf16 v[32:47], v[10:13], v[96:99], v[32:47]
	v_mfma_f32_32x32x16_bf16 v[16:31], v[112:115], v[96:99], v[16:31]
	v_exp_f32_e32 v2, v104
	v_exp_f32_e32 v4, v105
	v_exp_f32_e32 v3, v106
	v_exp_f32_e32 v5, v107
	v_exp_f32_e32 v6, v108
	v_exp_f32_e32 v8, v109
	v_exp_f32_e32 v7, v110
	v_exp_f32_e32 v9, v111
	v_pk_add_f32 v[10:11], v[2:3], v[4:5]
	v_add_u32_e32 v0, s1, v180
	v_pk_add_f32 v[14:15], v[10:11], v[10:11] op_sel_hi:[0,1]
	v_pk_add_f32 v[10:11], v[6:7], v[8:9]
	v_cvt_pk_bf16_f32 v2, v2, v4
	v_pk_add_f32 v[112:113], v[10:11], v[10:11] op_sel_hi:[0,1]
	v_cvt_pk_bf16_f32 v3, v3, v5
	v_cvt_pk_bf16_f32 v4, v6, v8
	v_cvt_pk_bf16_f32 v5, v7, v9
	ds_read_b128 v[6:9], v0 offset:24576
	ds_read_b128 v[10:13], v0 offset:28672
	ds_read_b128 v[96:99], v0 offset:32768
	ds_read_b128 v[104:107], v0 offset:36864
	v_mfma_f32_32x32x16_bf16 v[64:79], v[100:103], v[2:5], v[64:79]
	v_mfma_f32_32x32x16_bf16 v[48:63], v[116:119], v[2:5], v[48:63]
	v_mfma_f32_32x32x16_bf16 v[32:47], v[120:123], v[2:5], v[32:47]
	v_mfma_f32_32x32x16_bf16 v[16:31], v[124:127], v[2:5], v[16:31]
	v_exp_f32_e32 v0, v80
	v_exp_f32_e32 v2, v81
	v_exp_f32_e32 v3, v82
	v_exp_f32_e32 v4, v83
	v_exp_f32_e32 v5, v84
	v_exp_f32_e32 v14, v85
	v_exp_f32_e32 v80, v86
	v_exp_f32_e32 v81, v87
	v_add_f32_e32 v115, v0, v2
	v_cvt_pk_bf16_f32 v2, v0, v2
	v_add_u32_e32 v0, s1, v175
	v_add_f32_e32 v117, v3, v4
	v_add_f32_e32 v119, v5, v14
	v_add_f32_e32 v121, v80, v81
	v_cvt_pk_bf16_f32 v3, v3, v4
	v_cvt_pk_bf16_f32 v4, v5, v14
	v_cvt_pk_bf16_f32 v5, v80, v81
	ds_read_b128 v[80:83], v0 offset:24576
	ds_read_b128 v[84:87], v0 offset:28672
	ds_read_b128 v[100:103], v0 offset:32768
	ds_read_b128 v[108:111], v0 offset:36864
	s_waitcnt lgkmcnt(0)
	v_mfma_f32_32x32x16_bf16 v[64:79], v[6:9], v[2:5], v[64:79]
	v_mfma_f32_32x32x16_bf16 v[48:63], v[10:13], v[2:5], v[48:63]
	v_mfma_f32_32x32x16_bf16 v[32:47], v[96:99], v[2:5], v[32:47]
	v_mfma_f32_32x32x16_bf16 v[16:31], v[104:107], v[2:5], v[16:31]
	v_exp_f32_e32 v114, v88
	v_exp_f32_e32 v116, v89
	v_exp_f32_e32 v118, v90
	v_exp_f32_e32 v120, v91
	v_exp_f32_e32 v14, v92
	v_exp_f32_e32 v112, v93
	v_exp_f32_e32 v128, v94
	v_exp_f32_e32 v0, v95
	v_cvt_pk_bf16_f32 v2, v114, v116
	v_cvt_pk_bf16_f32 v3, v118, v120
	v_cvt_pk_bf16_f32 v4, v14, v112
	v_cvt_pk_bf16_f32 v5, v128, v0
	v_pk_add_f32 v[6:7], v[114:115], v[116:117]
	v_pk_add_f32 v[8:9], v[118:119], v[120:121]
	v_pk_add_f32 v[10:11], v[128:129], v[0:1]
	v_pk_add_f32 v[6:7], v[6:7], v[8:9]
	v_pk_add_f32 v[8:9], v[14:15], v[112:113]
	v_mfma_f32_32x32x16_bf16 v[64:79], v[80:83], v[2:5], v[64:79]
	v_add_f32_e64 v8, v8, v10
	v_add_f32_e64 v9, v9, v11
	v_add_f32_e64 v6, v6, v8
	v_add_f32_e64 v7, v7, v9
	v_pk_add_f32 v[6:7], v[6:7], v[6:7] op_sel:[0,1] op_sel_hi:[1,0]
	v_mfma_f32_32x32x16_bf16 v[48:63], v[84:87], v[2:5], v[48:63]
	v_mfma_f32_32x32x16_bf16 v[32:47], v[100:103], v[2:5], v[32:47]
	v_mfma_f32_32x32x16_bf16 v[16:31], v[108:111], v[2:5], v[16:31]
	v_mov_b32_e32 v0, v6
	s_barrier
; #define GAS __attribute__((address_space(1)))
; template <int TYPE>
; __device__ __forceinline__ void attn_mfma_unit2(const AttnCtx& A, unsigned char* ws, LAS unsigned char* lds, int tid, const AUnit& u) {
;     ...
;     __builtin_amdgcn_s_setprio(0);
;     ...
;     const float il = 1.0f / lrun;
;     const int lane_e = lane_id(), q_e = lane_e & 31, h2_e = lane_e >> 5, qrow_e = u.qrow0 + 32 * w + q_e;
;     if (TYPE == 2) {
;         __syncthreads();
;         LAS unsigned char* tb = lds + w * 16384;
; #pragma unroll
;         for (int d0 = 0; d0 < 4; ++d0)
; #pragma unroll
;             for (int i = 0; i < 4; ++i) {
; #pragma unroll
;                 for (int e = 0; e < 4; ++e) o[d0][4 * i + e] *= il;
;                 const f32x4 v = {o[d0][4 * i], o[d0][4 * i + 1], o[d0][4 * i + 2], o[d0][4 * i + 3]};
;                 *(LAS f32x4*)(tb + ((q_e * 32 + ((8 * d0 + 2 * i + h2_e) ^ q_e)) << 4)) = v;
;             }
;         LDS_WAIT(); asm volatile("" ::: "memory");
;         {
;             GAS unsigned long long* drow = (GAS unsigned long long*)((float*)(ws + WS_DTMP) + ((size_t)u.pass * M + u.qrow0 + 32 * w) * 640 + u.h * 128) + lane_e;
; #pragma unroll
;             for (int r = 0; r < 32; ++r) {
;                 const unsigned long long x = *(const LAS unsigned long long*)(tb + ((r * 32 + ((lane_e >> 1) ^ r)) << 4) + 8 * (lane_e & 1));
;                 __hip_atomic_store(drow + (size_t)r * 320, x, RLX_AGENT);
;             }
;         }
;         asm volatile("s_waitcnt vmcnt(0)" ::: "memory");
;         __syncthreads();
;         volatile LAS unsigned* misc = (volatile LAS unsigned*)(lds + MISC_OFF);
;         if (w == 0 && lane_e == 0) {
;             gu32* cnt = (gu32*)(ws + WS_CTL) + CW_DC + (u.isctx ? 160 + u.b * 5 + u.h : (u.b * 5 + u.h) * 16 + ((u.qrow0 - u.b * SEQ) >> 8));
;             misc[1] = __hip_atomic_fetch_add(cnt, 1u, RLX_AGENT);
;         }
;         __syncthreads();
;         if (misc[1] & 1u) {
;             GAS unsigned long long* orow = (GAS unsigned long long*)((float*)(ws + WS_DTMP) + ((size_t)(1 - u.pass) * M + u.qrow0 + 32 * w) * 640 + u.h * 128) + lane_e;
; #pragma unroll
;             for (int hh = 0; hh < 2; ++hh) {
;                 unsigned long long t[16];
; #pragma unroll
;                 for (int r = 0; r < 16; ++r) t[r] = __hip_atomic_load(orow + (size_t)(16 * hh + r) * 320, RLX_AGENT);
; #pragma unroll
	s_nop 0
	v_permlane32_swap_b32_e32 v6, v0
	v_add_f32_e32 v0, v6, v0
	v_add_f32_e32 v0, v171, v0
	s_setprio 0
	v_div_scale_f32 v2, s[0:1], v0, v0, 1.0
	v_rcp_f32_e32 v3, v2
	v_div_scale_f32 v4, vcc, 1.0, v0, 1.0
	v_readlane_b32 s14, v254, 21
	v_fma_f32 v5, -v2, v3, 1.0
	v_fmac_f32_e32 v3, v5, v3
	v_mul_f32_e32 v5, v4, v3
	v_fma_f32 v6, -v2, v5, v4
	v_fmac_f32_e32 v5, v6, v3
	v_fma_f32 v2, -v2, v5, v4
	v_div_fmas_f32 v2, v2, v3, v5
	v_div_fixup_f32 v0, v2, v0, 1.0
	v_mbcnt_lo_u32_b32 v4, -1, 0
	v_mbcnt_hi_u32_b32 v4, -1, v4
	v_pk_mul_f32 v[6:7], v[66:67], v[0:1] op_sel_hi:[1,0]
	v_and_b32_e32 v2, 31, v4
	v_add_u32_e32 v2, s6, v2
	v_ashrrev_i32_e32 v3, 31, v2
	v_lshlrev_b64 v[2:3], 12, v[2:3]
	v_ashrrev_i32_e32 v4, 3, v4
	v_lshl_add_u64 v[2:3], s[94:95], 0, v[2:3]
	v_and_b32_e32 v4, -4, v4
	v_lshl_add_u64 v[2:3], s[2:3], 1, v[2:3]
	v_ashrrev_i32_e32 v5, 31, v4
	v_lshl_add_u64 v[2:3], v[4:5], 1, v[2:3]
	v_pk_mul_f32 v[4:5], v[64:65], v[0:1] op_sel_hi:[1,0]
	s_nop 0
	v_cvt_pk_bf16_f32 v4, v4, v5
	v_cvt_pk_bf16_f32 v5, v6, v7
	global_store_dwordx2 v[2:3], v[4:5], off offset:1536
	v_pk_mul_f32 v[4:5], v[68:69], v[0:1] op_sel_hi:[1,0]
	v_pk_mul_f32 v[6:7], v[70:71], v[0:1] op_sel_hi:[1,0]
	v_cvt_pk_bf16_f32 v4, v4, v5
	v_cvt_pk_bf16_f32 v5, v6, v7
	global_store_dwordx2 v[2:3], v[4:5], off offset:1552
	v_pk_mul_f32 v[4:5], v[72:73], v[0:1] op_sel_hi:[1,0]
	v_pk_mul_f32 v[6:7], v[74:75], v[0:1] op_sel_hi:[1,0]
	v_cvt_pk_bf16_f32 v4, v4, v5
	v_cvt_pk_bf16_f32 v5, v6, v7
	global_store_dwordx2 v[2:3], v[4:5], off offset:1568
	v_pk_mul_f32 v[4:5], v[76:77], v[0:1] op_sel_hi:[1,0]
	v_pk_mul_f32 v[6:7], v[78:79], v[0:1] op_sel_hi:[1,0]
	v_cvt_pk_bf16_f32 v4, v4, v5
	v_cvt_pk_bf16_f32 v5, v6, v7
	global_store_dwordx2 v[2:3], v[4:5], off offset:1584
	v_pk_mul_f32 v[4:5], v[48:49], v[0:1] op_sel_hi:[1,0]
	v_pk_mul_f32 v[6:7], v[50:51], v[0:1] op_sel_hi:[1,0]
	v_cvt_pk_bf16_f32 v4, v4, v5
	v_cvt_pk_bf16_f32 v5, v6, v7
	global_store_dwordx2 v[2:3], v[4:5], off offset:1600
	v_pk_mul_f32 v[4:5], v[52:53], v[0:1] op_sel_hi:[1,0]
	v_pk_mul_f32 v[6:7], v[54:55], v[0:1] op_sel_hi:[1,0]
	v_cvt_pk_bf16_f32 v4, v4, v5
	v_cvt_pk_bf16_f32 v5, v6, v7
	global_store_dwordx2 v[2:3], v[4:5], off offset:1616
	v_pk_mul_f32 v[4:5], v[56:57], v[0:1] op_sel_hi:[1,0]
	v_pk_mul_f32 v[6:7], v[58:59], v[0:1] op_sel_hi:[1,0]
	v_cvt_pk_bf16_f32 v4, v4, v5
	v_cvt_pk_bf16_f32 v5, v6, v7
	global_store_dwordx2 v[2:3], v[4:5], off offset:1632
	v_pk_mul_f32 v[4:5], v[60:61], v[0:1] op_sel_hi:[1,0]
	v_pk_mul_f32 v[6:7], v[62:63], v[0:1] op_sel_hi:[1,0]
	v_cvt_pk_bf16_f32 v4, v4, v5
	v_cvt_pk_bf16_f32 v5, v6, v7
	global_store_dwordx2 v[2:3], v[4:5], off offset:1648
	v_pk_mul_f32 v[4:5], v[32:33], v[0:1] op_sel_hi:[1,0]
	v_pk_mul_f32 v[6:7], v[34:35], v[0:1] op_sel_hi:[1,0]
	v_cvt_pk_bf16_f32 v4, v4, v5
	v_cvt_pk_bf16_f32 v5, v6, v7
	global_store_dwordx2 v[2:3], v[4:5], off offset:1664
	v_pk_mul_f32 v[4:5], v[36:37], v[0:1] op_sel_hi:[1,0]
	v_pk_mul_f32 v[6:7], v[38:39], v[0:1] op_sel_hi:[1,0]
	v_cvt_pk_bf16_f32 v4, v4, v5
	v_cvt_pk_bf16_f32 v5, v6, v7
	global_store_dwordx2 v[2:3], v[4:5], off offset:1680
	v_pk_mul_f32 v[4:5], v[40:41], v[0:1] op_sel_hi:[1,0]
	v_pk_mul_f32 v[6:7], v[42:43], v[0:1] op_sel_hi:[1,0]
	v_cvt_pk_bf16_f32 v4, v4, v5
	v_cvt_pk_bf16_f32 v5, v6, v7
	global_store_dwordx2 v[2:3], v[4:5], off offset:1696
	v_pk_mul_f32 v[4:5], v[44:45], v[0:1] op_sel_hi:[1,0]
	v_pk_mul_f32 v[6:7], v[46:47], v[0:1] op_sel_hi:[1,0]
	v_cvt_pk_bf16_f32 v4, v4, v5
	v_cvt_pk_bf16_f32 v5, v6, v7
	global_store_dwordx2 v[2:3], v[4:5], off offset:1712
	v_pk_mul_f32 v[4:5], v[16:17], v[0:1] op_sel_hi:[1,0]
	v_pk_mul_f32 v[6:7], v[18:19], v[0:1] op_sel_hi:[1,0]
	v_cvt_pk_bf16_f32 v4, v4, v5
	v_cvt_pk_bf16_f32 v5, v6, v7
	global_store_dwordx2 v[2:3], v[4:5], off offset:1728
	v_pk_mul_f32 v[4:5], v[20:21], v[0:1] op_sel_hi:[1,0]
	v_pk_mul_f32 v[6:7], v[22:23], v[0:1] op_sel_hi:[1,0]
	v_cvt_pk_bf16_f32 v4, v4, v5
	v_cvt_pk_bf16_f32 v5, v6, v7
	global_store_dwordx2 v[2:3], v[4:5], off offset:1744
	v_pk_mul_f32 v[4:5], v[24:25], v[0:1] op_sel_hi:[1,0]
	v_pk_mul_f32 v[6:7], v[26:27], v[0:1] op_sel_hi:[1,0]
	v_cvt_pk_bf16_f32 v4, v4, v5
	v_cvt_pk_bf16_f32 v5, v6, v7
	global_store_dwordx2 v[2:3], v[4:5], off offset:1760
	v_pk_mul_f32 v[4:5], v[28:29], v[0:1] op_sel_hi:[1,0]
	v_pk_mul_f32 v[6:7], v[30:31], v[0:1] op_sel_hi:[1,0]
	v_cvt_pk_bf16_f32 v4, v4, v5
	v_cvt_pk_bf16_f32 v5, v6, v7
	global_store_dwordx2 v[2:3], v[4:5], off offset:1776
	s_branch .LBB0_2746

; __global__ void __launch_bounds__(NTHREADS, 2) dit_fwd(Args args) {
	.amdhsa_kernel _Z7dit_fwd4Args
		.amdhsa_group_segment_fixed_size 0
		.amdhsa_private_segment_fixed_size 0
		.amdhsa_kernarg_size 440
		.amdhsa_user_sgpr_count 2
		.amdhsa_user_sgpr_dispatch_ptr 0
		.amdhsa_user_sgpr_queue_ptr 0
		.amdhsa_user_sgpr_kernarg_segment_ptr 1
		.amdhsa_user_sgpr_dispatch_id 0
		.amdhsa_user_sgpr_kernarg_preload_length 0
		.amdhsa_user_sgpr_kernarg_preload_offset 0
		.amdhsa_user_sgpr_private_segment_size 0
		.amdhsa_uses_dynamic_stack 0
		.amdhsa_enable_private_segment 0
		.amdhsa_system_sgpr_workgroup_id_x 1
		.amdhsa_system_sgpr_workgroup_id_y 0
		.amdhsa_system_sgpr_workgroup_id_z 0
		.amdhsa_system_sgpr_workgroup_info 0
		.amdhsa_system_vgpr_workitem_id 0
		.amdhsa_next_free_vgpr 256
		.amdhsa_next_free_sgpr 102
		.amdhsa_accum_offset 256
		.amdhsa_reserve_vcc 1
		.amdhsa_float_round_mode_32 0
		.amdhsa_float_round_mode_16_64 0
		.amdhsa_float_denorm_mode_32 3
		.amdhsa_float_denorm_mode_16_64 3
		.amdhsa_dx10_clamp 1
		.amdhsa_ieee_mode 1
		.amdhsa_fp16_overflow 0
		.amdhsa_tg_split 0
		.amdhsa_exception_fp_ieee_invalid_op 0
		.amdhsa_exception_fp_denorm_src 0
		.amdhsa_exception_fp_ieee_div_zero 0
		.amdhsa_exception_fp_ieee_overflow 0
		.amdhsa_exception_fp_ieee_underflow 0
		.amdhsa_exception_fp_ieee_inexact 0
		.amdhsa_exception_int_div_zero 0
	.end_amdhsa_kernel

; __global__ void __launch_bounds__(NTHREADS, 2) dit_fwd(Args args) {
amdhsa.kernels:
  - .agpr_count:     0
    .args:
      - .offset:         0
        .size:           184
        .value_kind:     by_value
      - .offset:         184
        .size:           4
        .value_kind:     hidden_block_count_x
      - .offset:         188
        .size:           4
        .value_kind:     hidden_block_count_y
      - .offset:         192
        .size:           4
        .value_kind:     hidden_block_count_z
      - .offset:         196
        .size:           2
        .value_kind:     hidden_group_size_x
      - .offset:         198
        .size:           2
        .value_kind:     hidden_group_size_y
      - .offset:         200
        .size:           2
        .value_kind:     hidden_group_size_z
      - .offset:         202
        .size:           2
        .value_kind:     hidden_remainder_x
      - .offset:         204
        .size:           2
        .value_kind:     hidden_remainder_y
      - .offset:         206
        .size:           2
        .value_kind:     hidden_remainder_z
      - .offset:         224
        .size:           8
        .value_kind:     hidden_global_offset_x
      - .offset:         232
        .size:           8
        .value_kind:     hidden_global_offset_y
      - .offset:         240
        .size:           8
        .value_kind:     hidden_global_offset_z
      - .offset:         248
        .size:           2
        .value_kind:     hidden_grid_dims
      - .offset:         304
        .size:           4
        .value_kind:     hidden_dynamic_lds_size
    .group_segment_fixed_size: 0
    .kernarg_segment_align: 8
    .kernarg_segment_size: 440
    .language:       OpenCL C
    .language_version:
      - 2
      - 0
    .max_flat_workgroup_size: 512
    .name:           _Z7dit_fwd4Args
    .private_segment_fixed_size: 0
    .sgpr_count:     108
    .sgpr_spill_count: 393
    .symbol:         _Z7dit_fwd4Args.kd
    .uniform_work_group_size: 1
    .uses_dynamic_stack: false
    .vgpr_count:     256
    .vgpr_spill_count: 0
    .wavefront_size: 64
